# unit entry: first-segment LDS reads issued before the accumulator zero-init, zero-init with 64-bit moves; FFN-in epilogue store addresses derived from the first one
# speedup vs baseline: 1.0168x; 1.0094x over previous
.LBB0_445:
	s_add_u32 s56, s62, 0xb0080
	s_addc_u32 s57, s63, 0
	s_add_u32 s62, s60, 0x100
	v_mov_b32_e32 v2, 0
	s_addc_u32 s63, s61, 0
	s_mov_b32 s84, -2
	s_waitcnt lgkmcnt(0)
	s_add_i32 s22, 0, 0x10000
	s_add_i32 s23, 0, 0x14000
	v_add_u32_e32 v134, s22, v191
	v_add_u32_e32 v162, s23, v191
	ds_read_b128 v[114:117], v134
	ds_read_b128 v[126:129], v134 offset:1024
	ds_read_b128 v[130:133], v134 offset:2048
	ds_read_b128 v[134:137], v134 offset:3072
	ds_read_b128 v[146:149], v162
	ds_read_b128 v[150:153], v162 offset:1024
	ds_read_b128 v[158:161], v162 offset:2048
	ds_read_b128 v[182:185], v162 offset:3072
	ds_read_b128 v[186:189], v193
	ds_read_b128 v[194:197], v193 offset:1024
	ds_read_b128 v[198:201], v193 offset:2048
	ds_read_b128 v[214:217], v193 offset:3072
	ds_read_b128 v[218:221], v193 offset:4096
	ds_read_b128 v[222:225], v193 offset:5120
	ds_read_b128 v[226:229], v193 offset:6144
	ds_read_b128 v[230:233], v193 offset:7168
	v_mov_b32_e32 v3, 0
	v_mov_b64_e32 v[4:5], 0
	v_mov_b64_e32 v[6:7], 0
	v_mov_b64_e32 v[8:9], 0
	v_mov_b64_e32 v[10:11], 0
	v_mov_b64_e32 v[12:13], 0
	v_mov_b64_e32 v[14:15], 0
	v_mov_b64_e32 v[16:17], 0
	v_mov_b64_e32 v[18:19], 0
	v_mov_b64_e32 v[20:21], 0
	v_mov_b64_e32 v[22:23], 0
	v_mov_b64_e32 v[24:25], 0
	v_mov_b64_e32 v[26:27], 0
	v_mov_b64_e32 v[28:29], 0
	v_mov_b64_e32 v[30:31], 0
	v_mov_b64_e32 v[32:33], 0
	v_mov_b64_e32 v[34:35], 0
	v_mov_b64_e32 v[36:37], 0
	v_mov_b64_e32 v[38:39], 0
	v_mov_b64_e32 v[40:41], 0
	v_mov_b64_e32 v[42:43], 0
	v_mov_b64_e32 v[44:45], 0
	v_mov_b64_e32 v[46:47], 0
	v_mov_b64_e32 v[48:49], 0
	v_mov_b64_e32 v[50:51], 0
	v_mov_b64_e32 v[52:53], 0
	v_mov_b64_e32 v[54:55], 0
	v_mov_b64_e32 v[56:57], 0
	v_mov_b64_e32 v[58:59], 0
	v_mov_b64_e32 v[60:61], 0
	v_mov_b64_e32 v[62:63], 0
	v_mov_b64_e32 v[64:65], 0
	v_mov_b64_e32 v[66:67], 0
	v_mov_b64_e32 v[68:69], 0
	v_mov_b64_e32 v[70:71], 0
	v_mov_b64_e32 v[72:73], 0
	v_mov_b64_e32 v[74:75], 0
	v_mov_b64_e32 v[76:77], 0
	v_mov_b64_e32 v[78:79], 0
	v_mov_b64_e32 v[80:81], 0
	v_mov_b64_e32 v[82:83], 0
	v_mov_b64_e32 v[84:85], 0
	v_mov_b64_e32 v[86:87], 0
	v_mov_b64_e32 v[88:89], 0
	v_mov_b64_e32 v[90:91], 0
	v_mov_b64_e32 v[92:93], 0
	v_mov_b64_e32 v[94:95], 0
	v_mov_b64_e32 v[96:97], 0
	v_mov_b64_e32 v[98:99], 0
	v_mov_b64_e32 v[100:101], 0
	v_mov_b64_e32 v[102:103], 0
	v_mov_b64_e32 v[104:105], 0
	v_mov_b64_e32 v[106:107], 0
	v_mov_b64_e32 v[108:109], 0
	v_mov_b64_e32 v[110:111], 0
	v_mov_b64_e32 v[112:113], 0
	v_mov_b64_e32 v[118:119], 0
	v_mov_b64_e32 v[120:121], 0
	v_mov_b64_e32 v[122:123], 0
	v_mov_b64_e32 v[124:125], 0
	v_mov_b64_e32 v[138:139], 0
	v_mov_b64_e32 v[140:141], 0
	v_mov_b64_e32 v[142:143], 0
	v_mov_b64_e32 v[144:145], 0
	s_mov_b64 s[12:13], 0xb0000
	s_mov_b64 s[86:87], 0x108000
	s_mov_b64 s[96:97], 0x58080
	s_mov_b64 vcc, 0xb0080
	s_mov_b64 s[0:1], 0x108080
	s_branch .Lmid_446
	.p2alignl 6, 3212836864

.Lmid_446:
	s_add_u32 s20, s56, 0xfff50080
	s_addc_u32 s21, s57, -1
	s_cmp_eq_u32 s84, 40
	s_cselect_b32 s61, s49, s21
	s_cselect_b32 s60, s48, s20
	s_cselect_b32 s21, s51, s63
	s_cselect_b32 s20, s50, s62
	v_lshl_add_u64 v[162:163], s[56:57], 0, v[156:157]
	s_add_i32 m0, s47, 0xc000
	s_nop 0
	global_load_lds_dwordx4 v[162:163], off
	v_lshl_add_u64 v[162:163], v[162:163], 0, s[2:3]
	s_add_i32 m0, s47, 0xe000
	s_nop 0
	global_load_lds_dwordx4 v[162:163], off
	s_waitcnt vmcnt(8)
	s_waitcnt lgkmcnt(0)
	s_barrier
	s_setprio 1
	s_waitcnt lgkmcnt(0)
	v_mfma_f32_16x16x32_bf16 v[142:145], v[114:117], v[186:189], v[142:145]
	v_mfma_f32_16x16x32_bf16 v[142:145], v[126:129], v[194:197], v[142:145]
	v_mfma_f32_16x16x32_bf16 v[138:141], v[130:133], v[186:189], v[138:141]
	v_mfma_f32_16x16x32_bf16 v[138:141], v[134:137], v[194:197], v[138:141]
	v_mfma_f32_16x16x32_bf16 v[110:113], v[114:117], v[198:201], v[110:113]
	v_mfma_f32_16x16x32_bf16 v[110:113], v[126:129], v[214:217], v[110:113]
	v_mfma_f32_16x16x32_bf16 v[106:109], v[130:133], v[198:201], v[106:109]
	v_mfma_f32_16x16x32_bf16 v[106:109], v[134:137], v[214:217], v[106:109]
	v_mfma_f32_16x16x32_bf16 v[94:97], v[114:117], v[218:221], v[94:97]
	v_mfma_f32_16x16x32_bf16 v[94:97], v[126:129], v[222:225], v[94:97]
	v_mfma_f32_16x16x32_bf16 v[90:93], v[130:133], v[218:221], v[90:93]
	v_mfma_f32_16x16x32_bf16 v[90:93], v[134:137], v[222:225], v[90:93]
	v_mfma_f32_16x16x32_bf16 v[78:81], v[114:117], v[226:229], v[78:81]
	v_mfma_f32_16x16x32_bf16 v[78:81], v[126:129], v[230:233], v[78:81]
	v_mfma_f32_16x16x32_bf16 v[74:77], v[130:133], v[226:229], v[74:77]
	v_mfma_f32_16x16x32_bf16 v[74:77], v[134:137], v[230:233], v[74:77]
	s_setprio 0
	s_setprio 1
	v_mfma_f32_16x16x32_bf16 v[122:125], v[146:149], v[186:189], v[122:125]
	v_mfma_f32_16x16x32_bf16 v[122:125], v[150:153], v[194:197], v[122:125]
	v_mfma_f32_16x16x32_bf16 v[118:121], v[158:161], v[186:189], v[118:121]
	v_mfma_f32_16x16x32_bf16 v[118:121], v[182:185], v[194:197], v[118:121]
	v_mfma_f32_16x16x32_bf16 v[102:105], v[146:149], v[198:201], v[102:105]
	v_mfma_f32_16x16x32_bf16 v[102:105], v[150:153], v[214:217], v[102:105]
	v_mfma_f32_16x16x32_bf16 v[98:101], v[158:161], v[198:201], v[98:101]
	v_mfma_f32_16x16x32_bf16 v[98:101], v[182:185], v[214:217], v[98:101]
	v_mfma_f32_16x16x32_bf16 v[86:89], v[146:149], v[218:221], v[86:89]
	v_mfma_f32_16x16x32_bf16 v[86:89], v[150:153], v[222:225], v[86:89]
	v_mfma_f32_16x16x32_bf16 v[82:85], v[158:161], v[218:221], v[82:85]
	v_mfma_f32_16x16x32_bf16 v[82:85], v[182:185], v[222:225], v[82:85]
	v_mfma_f32_16x16x32_bf16 v[70:73], v[146:149], v[226:229], v[70:73]
	v_mfma_f32_16x16x32_bf16 v[70:73], v[150:153], v[230:233], v[70:73]
	v_mfma_f32_16x16x32_bf16 v[66:69], v[158:161], v[226:229], v[66:69]
	v_mfma_f32_16x16x32_bf16 v[66:69], v[182:185], v[230:233], v[66:69]
	s_setprio 0
	s_barrier
	ds_read_b128 v[186:189], v193 offset:16384
	ds_read_b128 v[194:197], v193 offset:17408
	ds_read_b128 v[198:201], v193 offset:18432
	ds_read_b128 v[214:217], v193 offset:19456
	ds_read_b128 v[218:221], v193 offset:20480
	ds_read_b128 v[222:225], v193 offset:21504
	ds_read_b128 v[226:229], v193 offset:22528
	ds_read_b128 v[230:233], v193 offset:23552
	v_lshl_add_u64 v[162:163], s[20:21], 0, v[0:1]
	s_add_i32 s20, s22, s46
	s_mov_b32 m0, s20
	s_nop 0
	global_load_lds_dwordx4 v[162:163], off
	v_lshl_add_u64 v[202:203], v[162:163], 0, s[2:3]
	s_add_i32 m0, s20, 0x2000
	s_add_i32 s20, s23, s46
	global_load_lds_dwordx4 v[202:203], off
	v_lshl_add_u64 v[202:203], v[162:163], 0, s[12:13]
	s_mov_b32 m0, s20
	s_nop 0
	global_load_lds_dwordx4 v[202:203], off
	v_lshl_add_u64 v[202:203], v[162:163], 0, s[86:87]
	s_add_i32 m0, s20, 0x2000
	s_nop 0
	global_load_lds_dwordx4 v[202:203], off
	v_lshl_add_u64 v[202:203], s[60:61], 0, v[154:155]
	s_mov_b32 m0, s47
	v_lshl_add_u64 v[234:235], v[202:203], 0, s[2:3]
	global_load_lds_dwordx4 v[202:203], off
	s_mov_b32 m0, s68
	s_nop 0
	global_load_lds_dwordx4 v[234:235], off
	s_waitcnt vmcnt(8)
	s_waitcnt lgkmcnt(0)
	s_barrier
	s_setprio 1
	s_waitcnt lgkmcnt(0)
	v_mfma_f32_16x16x32_bf16 v[62:65], v[114:117], v[186:189], v[62:65]
	v_mfma_f32_16x16x32_bf16 v[62:65], v[126:129], v[194:197], v[62:65]
	v_mfma_f32_16x16x32_bf16 v[58:61], v[130:133], v[186:189], v[58:61]
	v_mfma_f32_16x16x32_bf16 v[58:61], v[134:137], v[194:197], v[58:61]
	v_mfma_f32_16x16x32_bf16 v[46:49], v[114:117], v[198:201], v[46:49]
	v_mfma_f32_16x16x32_bf16 v[46:49], v[126:129], v[214:217], v[46:49]
	v_mfma_f32_16x16x32_bf16 v[42:45], v[130:133], v[198:201], v[42:45]
	v_mfma_f32_16x16x32_bf16 v[42:45], v[134:137], v[214:217], v[42:45]
	v_mfma_f32_16x16x32_bf16 v[30:33], v[114:117], v[218:221], v[30:33]
	v_mfma_f32_16x16x32_bf16 v[30:33], v[126:129], v[222:225], v[30:33]
	v_mfma_f32_16x16x32_bf16 v[26:29], v[130:133], v[218:221], v[26:29]
	v_mfma_f32_16x16x32_bf16 v[26:29], v[134:137], v[222:225], v[26:29]
	v_mfma_f32_16x16x32_bf16 v[14:17], v[114:117], v[226:229], v[14:17]
	v_mfma_f32_16x16x32_bf16 v[14:17], v[126:129], v[230:233], v[14:17]
	v_mfma_f32_16x16x32_bf16 v[10:13], v[130:133], v[226:229], v[10:13]
	v_mfma_f32_16x16x32_bf16 v[10:13], v[134:137], v[230:233], v[10:13]
	s_setprio 0
	s_setprio 1
	v_mfma_f32_16x16x32_bf16 v[54:57], v[146:149], v[186:189], v[54:57]
	v_mfma_f32_16x16x32_bf16 v[54:57], v[150:153], v[194:197], v[54:57]
	v_mfma_f32_16x16x32_bf16 v[50:53], v[158:161], v[186:189], v[50:53]
	v_mfma_f32_16x16x32_bf16 v[50:53], v[182:185], v[194:197], v[50:53]
	v_mfma_f32_16x16x32_bf16 v[38:41], v[146:149], v[198:201], v[38:41]
	v_mfma_f32_16x16x32_bf16 v[38:41], v[150:153], v[214:217], v[38:41]
	v_mfma_f32_16x16x32_bf16 v[34:37], v[158:161], v[198:201], v[34:37]
	v_mfma_f32_16x16x32_bf16 v[34:37], v[182:185], v[214:217], v[34:37]
	v_mfma_f32_16x16x32_bf16 v[22:25], v[146:149], v[218:221], v[22:25]
	v_mfma_f32_16x16x32_bf16 v[22:25], v[150:153], v[222:225], v[22:25]
	v_mfma_f32_16x16x32_bf16 v[18:21], v[158:161], v[218:221], v[18:21]
	v_mfma_f32_16x16x32_bf16 v[18:21], v[182:185], v[222:225], v[18:21]
	v_mfma_f32_16x16x32_bf16 v[6:9], v[146:149], v[226:229], v[6:9]
	v_mfma_f32_16x16x32_bf16 v[6:9], v[150:153], v[230:233], v[6:9]
	v_mfma_f32_16x16x32_bf16 v[2:5], v[158:161], v[226:229], v[2:5]
	v_mfma_f32_16x16x32_bf16 v[2:5], v[182:185], v[230:233], v[2:5]
	s_setprio 0
	s_barrier
	s_add_i32 s20, 0, 0x18000
	s_add_i32 s21, 0, 0x1c000
	v_add_u32_e32 v134, s20, v191
	v_add_u32_e32 v182, s21, v191
	ds_read_b128 v[114:117], v134
	ds_read_b128 v[126:129], v134 offset:1024
	ds_read_b128 v[130:133], v134 offset:2048
	ds_read_b128 v[134:137], v134 offset:3072
	ds_read_b128 v[146:149], v182
	ds_read_b128 v[150:153], v182 offset:1024
	ds_read_b128 v[158:161], v182 offset:2048
	ds_read_b128 v[182:185], v182 offset:3072
	ds_read_b128 v[186:189], v193 offset:32768
	ds_read_b128 v[194:197], v193 offset:33792
	ds_read_b128 v[198:201], v193 offset:34816
	ds_read_b128 v[214:217], v193 offset:35840
	ds_read_b128 v[218:221], v193 offset:36864
	ds_read_b128 v[222:225], v193 offset:37888
	ds_read_b128 v[226:229], v193 offset:38912
	ds_read_b128 v[230:233], v193 offset:39936
	s_mov_b32 m0, s69
	v_lshl_add_u64 v[234:235], v[202:203], 0, s[12:13]
	global_load_lds_dwordx4 v[234:235], off
	v_lshl_add_u64 v[234:235], v[202:203], 0, s[86:87]
	s_mov_b32 m0, s76
	s_nop 0
	global_load_lds_dwordx4 v[234:235], off
	s_waitcnt vmcnt(8)
	s_waitcnt lgkmcnt(0)
	s_barrier
	s_setprio 1
	s_waitcnt lgkmcnt(0)
	v_mfma_f32_16x16x32_bf16 v[142:145], v[114:117], v[186:189], v[142:145]
	v_mfma_f32_16x16x32_bf16 v[142:145], v[126:129], v[194:197], v[142:145]
	v_mfma_f32_16x16x32_bf16 v[138:141], v[130:133], v[186:189], v[138:141]
	v_mfma_f32_16x16x32_bf16 v[138:141], v[134:137], v[194:197], v[138:141]
	v_mfma_f32_16x16x32_bf16 v[110:113], v[114:117], v[198:201], v[110:113]
	v_mfma_f32_16x16x32_bf16 v[110:113], v[126:129], v[214:217], v[110:113]
	v_mfma_f32_16x16x32_bf16 v[106:109], v[130:133], v[198:201], v[106:109]
	v_mfma_f32_16x16x32_bf16 v[106:109], v[134:137], v[214:217], v[106:109]
	v_mfma_f32_16x16x32_bf16 v[94:97], v[114:117], v[218:221], v[94:97]
	v_mfma_f32_16x16x32_bf16 v[94:97], v[126:129], v[222:225], v[94:97]
	v_mfma_f32_16x16x32_bf16 v[90:93], v[130:133], v[218:221], v[90:93]
	v_mfma_f32_16x16x32_bf16 v[90:93], v[134:137], v[222:225], v[90:93]
	v_mfma_f32_16x16x32_bf16 v[78:81], v[114:117], v[226:229], v[78:81]
	v_mfma_f32_16x16x32_bf16 v[78:81], v[126:129], v[230:233], v[78:81]
	v_mfma_f32_16x16x32_bf16 v[74:77], v[130:133], v[226:229], v[74:77]
	v_mfma_f32_16x16x32_bf16 v[74:77], v[134:137], v[230:233], v[74:77]
	s_setprio 0
	s_setprio 1
	v_mfma_f32_16x16x32_bf16 v[122:125], v[146:149], v[186:189], v[122:125]
	v_mfma_f32_16x16x32_bf16 v[122:125], v[150:153], v[194:197], v[122:125]
	v_mfma_f32_16x16x32_bf16 v[118:121], v[158:161], v[186:189], v[118:121]
	v_mfma_f32_16x16x32_bf16 v[118:121], v[182:185], v[194:197], v[118:121]
	v_mfma_f32_16x16x32_bf16 v[102:105], v[146:149], v[198:201], v[102:105]
	v_mfma_f32_16x16x32_bf16 v[102:105], v[150:153], v[214:217], v[102:105]
	v_mfma_f32_16x16x32_bf16 v[98:101], v[158:161], v[198:201], v[98:101]
	v_mfma_f32_16x16x32_bf16 v[98:101], v[182:185], v[214:217], v[98:101]
	v_mfma_f32_16x16x32_bf16 v[86:89], v[146:149], v[218:221], v[86:89]
	v_mfma_f32_16x16x32_bf16 v[86:89], v[150:153], v[222:225], v[86:89]
	v_mfma_f32_16x16x32_bf16 v[82:85], v[158:161], v[218:221], v[82:85]
	v_mfma_f32_16x16x32_bf16 v[82:85], v[182:185], v[222:225], v[82:85]
	v_mfma_f32_16x16x32_bf16 v[70:73], v[146:149], v[226:229], v[70:73]
	v_mfma_f32_16x16x32_bf16 v[70:73], v[150:153], v[230:233], v[70:73]
	v_mfma_f32_16x16x32_bf16 v[66:69], v[158:161], v[226:229], v[66:69]
	v_mfma_f32_16x16x32_bf16 v[66:69], v[182:185], v[230:233], v[66:69]
	s_setprio 0
	s_barrier
	ds_read_b128 v[186:189], v193 offset:49152
	ds_read_b128 v[194:197], v193 offset:50176
	ds_read_b128 v[198:201], v193 offset:51200
	ds_read_b128 v[214:217], v193 offset:52224
	ds_read_b128 v[218:221], v193 offset:53248
	ds_read_b128 v[222:225], v193 offset:54272
	ds_read_b128 v[226:229], v193 offset:55296
	ds_read_b128 v[230:233], v193 offset:56320
	s_add_i32 s20, s20, s46
	v_lshl_add_u64 v[234:235], v[162:163], 0, s[34:35]
	s_mov_b32 m0, s20
	s_nop 0
	global_load_lds_dwordx4 v[234:235], off
	v_lshl_add_u64 v[234:235], v[162:163], 0, s[96:97]
	s_add_i32 m0, s20, 0x2000
	s_add_i32 s20, s21, s46
	global_load_lds_dwordx4 v[234:235], off
	v_lshl_add_u64 v[234:235], v[162:163], 0, vcc
	s_mov_b32 m0, s20
	v_lshl_add_u64 v[162:163], v[162:163], 0, s[0:1]
	global_load_lds_dwordx4 v[234:235], off
	s_add_i32 m0, s20, 0x2000
	s_nop 0
	global_load_lds_dwordx4 v[162:163], off
	v_lshl_add_u64 v[162:163], v[202:203], 0, s[34:35]
	s_mov_b32 m0, s77
	s_nop 0
	global_load_lds_dwordx4 v[162:163], off
	v_lshl_add_u64 v[162:163], v[202:203], 0, s[96:97]
	s_mov_b32 m0, s78
	s_nop 0
	global_load_lds_dwordx4 v[162:163], off
	s_waitcnt vmcnt(8)
	s_waitcnt lgkmcnt(0)
	s_barrier
	s_setprio 1
	s_waitcnt lgkmcnt(0)
	v_mfma_f32_16x16x32_bf16 v[62:65], v[114:117], v[186:189], v[62:65]
	v_mfma_f32_16x16x32_bf16 v[62:65], v[126:129], v[194:197], v[62:65]
	v_mfma_f32_16x16x32_bf16 v[58:61], v[130:133], v[186:189], v[58:61]
	v_mfma_f32_16x16x32_bf16 v[58:61], v[134:137], v[194:197], v[58:61]
	v_mfma_f32_16x16x32_bf16 v[46:49], v[114:117], v[198:201], v[46:49]
	v_mfma_f32_16x16x32_bf16 v[46:49], v[126:129], v[214:217], v[46:49]
	v_mfma_f32_16x16x32_bf16 v[42:45], v[130:133], v[198:201], v[42:45]
	v_mfma_f32_16x16x32_bf16 v[42:45], v[134:137], v[214:217], v[42:45]
	v_mfma_f32_16x16x32_bf16 v[30:33], v[114:117], v[218:221], v[30:33]
	v_mfma_f32_16x16x32_bf16 v[30:33], v[126:129], v[222:225], v[30:33]
	v_mfma_f32_16x16x32_bf16 v[26:29], v[130:133], v[218:221], v[26:29]
	v_mfma_f32_16x16x32_bf16 v[26:29], v[134:137], v[222:225], v[26:29]
	v_mfma_f32_16x16x32_bf16 v[14:17], v[114:117], v[226:229], v[14:17]
	v_mfma_f32_16x16x32_bf16 v[14:17], v[126:129], v[230:233], v[14:17]
	v_mfma_f32_16x16x32_bf16 v[10:13], v[130:133], v[226:229], v[10:13]
	v_mfma_f32_16x16x32_bf16 v[10:13], v[134:137], v[230:233], v[10:13]
	s_add_i32 s84, s84, 2
	s_add_u32 s56, s56, 0x100
	s_addc_u32 s57, s57, 0
	s_add_u32 s62, s62, 0x100
	s_addc_u32 s63, s63, 0
	s_setprio 0
	s_setprio 1
	v_mfma_f32_16x16x32_bf16 v[54:57], v[146:149], v[186:189], v[54:57]
	v_mfma_f32_16x16x32_bf16 v[54:57], v[150:153], v[194:197], v[54:57]
	v_mfma_f32_16x16x32_bf16 v[50:53], v[158:161], v[186:189], v[50:53]
	v_mfma_f32_16x16x32_bf16 v[50:53], v[182:185], v[194:197], v[50:53]
	v_mfma_f32_16x16x32_bf16 v[38:41], v[146:149], v[198:201], v[38:41]
	v_mfma_f32_16x16x32_bf16 v[38:41], v[150:153], v[214:217], v[38:41]
	v_mfma_f32_16x16x32_bf16 v[34:37], v[158:161], v[198:201], v[34:37]
	v_mfma_f32_16x16x32_bf16 v[34:37], v[182:185], v[214:217], v[34:37]
	v_mfma_f32_16x16x32_bf16 v[22:25], v[146:149], v[218:221], v[22:25]
	v_mfma_f32_16x16x32_bf16 v[22:25], v[150:153], v[222:225], v[22:25]
	v_mfma_f32_16x16x32_bf16 v[18:21], v[158:161], v[218:221], v[18:21]
	v_mfma_f32_16x16x32_bf16 v[18:21], v[182:185], v[222:225], v[18:21]
	v_mfma_f32_16x16x32_bf16 v[6:9], v[146:149], v[226:229], v[6:9]
	v_mfma_f32_16x16x32_bf16 v[6:9], v[150:153], v[230:233], v[6:9]
	v_mfma_f32_16x16x32_bf16 v[2:5], v[158:161], v[226:229], v[2:5]
	v_mfma_f32_16x16x32_bf16 v[2:5], v[182:185], v[230:233], v[2:5]
	s_setprio 0
	s_barrier
	s_cmp_gt_u32 s84, 41
	s_cbranch_scc0 .LBB0_446
	s_and_b64 vcc, exec, s[40:41]
	s_cbranch_vccz .LBB0_449
	s_barrier

.LBB0_487:
	s_ashr_i32 s57, s56, 31
	s_lshl_b64 s[20:21], s[56:57], 19
	s_add_u32 s60, s94, s20
	s_addc_u32 s61, s95, s21
	s_and_b64 s[20:21], s[54:55], exec
	s_cselect_b32 s57, s61, s69
	s_cselect_b32 s86, s60, s68
	s_ashr_i32 s51, s50, 31
	s_lshl_b64 s[20:21], s[50:51], 19
	s_add_u32 s62, s15, s20
	s_addc_u32 s63, s42, s21
	s_and_b64 s[20:21], s[54:55], exec
	s_cselect_b32 s51, s63, s77
	s_cselect_b32 s87, s62, s76
	s_add_u32 s68, s68, 0x40080
	s_addc_u32 s69, s69, 0
	s_add_u32 s91, s76, 0x100
	v_mov_b32_e32 v2, 0
	s_addc_u32 s96, s77, 0
	s_mov_b32 s97, -2
	s_add_i32 s22, 0, 0x10000
	v_add_u32_e32 v143, s22, v139
	s_add_i32 s23, 0, 0x14000
	ds_read_b128 v[134:137], v143
	ds_read_b128 v[144:147], v143 offset:1024
	ds_read_b128 v[148:151], v143 offset:2048
	ds_read_b128 v[152:155], v143 offset:3072
	v_add_u32_e32 v143, s23, v139
	ds_read_b128 v[156:159], v143
	ds_read_b128 v[160:163], v143 offset:1024
	ds_read_b128 v[182:185], v143 offset:2048
	ds_read_b128 v[186:189], v143 offset:3072
	ds_read_b128 v[190:193], v142
	ds_read_b128 v[194:197], v142 offset:1024
	ds_read_b128 v[198:201], v142 offset:2048
	ds_read_b128 v[214:217], v142 offset:3072
	ds_read_b128 v[218:221], v142 offset:4096
	ds_read_b128 v[222:225], v142 offset:5120
	ds_read_b128 v[226:229], v142 offset:6144
	ds_read_b128 v[230:233], v142 offset:7168
	v_mov_b32_e32 v3, 0
	v_mov_b64_e32 v[4:5], 0
	v_mov_b64_e32 v[6:7], 0
	v_mov_b64_e32 v[8:9], 0
	v_mov_b64_e32 v[10:11], 0
	v_mov_b64_e32 v[12:13], 0
	v_mov_b64_e32 v[14:15], 0
	v_mov_b64_e32 v[16:17], 0
	v_mov_b64_e32 v[18:19], 0
	v_mov_b64_e32 v[20:21], 0
	v_mov_b64_e32 v[22:23], 0
	v_mov_b64_e32 v[24:25], 0
	v_mov_b64_e32 v[26:27], 0
	v_mov_b64_e32 v[28:29], 0
	v_mov_b64_e32 v[30:31], 0
	v_mov_b64_e32 v[32:33], 0
	v_mov_b64_e32 v[34:35], 0
	v_mov_b64_e32 v[36:37], 0
	v_mov_b64_e32 v[38:39], 0
	v_mov_b64_e32 v[40:41], 0
	v_mov_b64_e32 v[42:43], 0
	v_mov_b64_e32 v[44:45], 0
	v_mov_b64_e32 v[46:47], 0
	v_mov_b64_e32 v[48:49], 0
	v_mov_b64_e32 v[50:51], 0
	v_mov_b64_e32 v[52:53], 0
	v_mov_b64_e32 v[54:55], 0
	v_mov_b64_e32 v[56:57], 0
	v_mov_b64_e32 v[58:59], 0
	v_mov_b64_e32 v[60:61], 0
	v_mov_b64_e32 v[62:63], 0
	v_mov_b64_e32 v[64:65], 0
	v_mov_b64_e32 v[66:67], 0
	v_mov_b64_e32 v[68:69], 0
	v_mov_b64_e32 v[70:71], 0
	v_mov_b64_e32 v[72:73], 0
	v_mov_b64_e32 v[74:75], 0
	v_mov_b64_e32 v[76:77], 0
	v_mov_b64_e32 v[78:79], 0
	v_mov_b64_e32 v[80:81], 0
	v_mov_b64_e32 v[82:83], 0
	v_mov_b64_e32 v[84:85], 0
	v_mov_b64_e32 v[86:87], 0
	v_mov_b64_e32 v[88:89], 0
	v_mov_b64_e32 v[90:91], 0
	v_mov_b64_e32 v[92:93], 0
	v_mov_b64_e32 v[94:95], 0
	v_mov_b64_e32 v[96:97], 0
	v_mov_b64_e32 v[98:99], 0
	v_mov_b64_e32 v[100:101], 0
	v_mov_b64_e32 v[102:103], 0
	v_mov_b64_e32 v[104:105], 0
	v_mov_b64_e32 v[106:107], 0
	v_mov_b64_e32 v[108:109], 0
	v_mov_b64_e32 v[110:111], 0
	v_mov_b64_e32 v[112:113], 0
	v_mov_b64_e32 v[114:115], 0
	v_mov_b64_e32 v[116:117], 0
	v_mov_b64_e32 v[118:119], 0
	v_mov_b64_e32 v[120:121], 0
	v_mov_b64_e32 v[122:123], 0
	v_mov_b64_e32 v[124:125], 0
	v_mov_b64_e32 v[126:127], 0
	v_mov_b64_e32 v[128:129], 0
	s_branch .Lmid_488
	.p2alignl 6, 3212836864

.Lmid_488:
	s_add_u32 s20, s68, 0xfffc0080
	s_addc_u32 s21, s69, -1
	s_cmp_eq_u32 s97, 12
	s_cselect_b32 s77, s57, s21
	s_cselect_b32 s76, s86, s20
	s_cselect_b32 s21, s51, s96
	s_cselect_b32 s20, s87, s91
	v_lshl_add_u64 v[202:203], s[68:69], 0, v[132:133]
	s_add_i32 m0, s43, 0xc000
	s_nop 0
	global_load_lds_dwordx4 v[202:203], off
	v_lshl_add_u64 v[202:203], v[202:203], 0, s[72:73]
	s_add_i32 m0, s43, 0xe000
	s_nop 0
	global_load_lds_dwordx4 v[202:203], off
	s_waitcnt vmcnt(8)
	s_waitcnt lgkmcnt(0)
	s_barrier
	s_setprio 1
	s_waitcnt lgkmcnt(0)
	v_mfma_f32_16x16x32_bf16 v[126:129], v[134:137], v[190:193], v[126:129]
	v_mfma_f32_16x16x32_bf16 v[126:129], v[144:147], v[194:197], v[126:129]
	v_mfma_f32_16x16x32_bf16 v[114:117], v[148:151], v[190:193], v[114:117]
	v_mfma_f32_16x16x32_bf16 v[114:117], v[152:155], v[194:197], v[114:117]
	v_mfma_f32_16x16x32_bf16 v[110:113], v[134:137], v[198:201], v[110:113]
	v_mfma_f32_16x16x32_bf16 v[110:113], v[144:147], v[214:217], v[110:113]
	v_mfma_f32_16x16x32_bf16 v[98:101], v[148:151], v[198:201], v[98:101]
	v_mfma_f32_16x16x32_bf16 v[98:101], v[152:155], v[214:217], v[98:101]
	v_mfma_f32_16x16x32_bf16 v[94:97], v[134:137], v[218:221], v[94:97]
	v_mfma_f32_16x16x32_bf16 v[94:97], v[144:147], v[222:225], v[94:97]
	v_mfma_f32_16x16x32_bf16 v[82:85], v[148:151], v[218:221], v[82:85]
	v_mfma_f32_16x16x32_bf16 v[82:85], v[152:155], v[222:225], v[82:85]
	v_mfma_f32_16x16x32_bf16 v[78:81], v[134:137], v[226:229], v[78:81]
	v_mfma_f32_16x16x32_bf16 v[78:81], v[144:147], v[230:233], v[78:81]
	v_mfma_f32_16x16x32_bf16 v[66:69], v[148:151], v[226:229], v[66:69]
	v_mfma_f32_16x16x32_bf16 v[66:69], v[152:155], v[230:233], v[66:69]
	s_setprio 0
	s_setprio 1
	v_mfma_f32_16x16x32_bf16 v[122:125], v[156:159], v[190:193], v[122:125]
	v_mfma_f32_16x16x32_bf16 v[122:125], v[160:163], v[194:197], v[122:125]
	v_mfma_f32_16x16x32_bf16 v[118:121], v[182:185], v[190:193], v[118:121]
	v_mfma_f32_16x16x32_bf16 v[118:121], v[186:189], v[194:197], v[118:121]
	v_mfma_f32_16x16x32_bf16 v[106:109], v[156:159], v[198:201], v[106:109]
	v_mfma_f32_16x16x32_bf16 v[106:109], v[160:163], v[214:217], v[106:109]
	v_mfma_f32_16x16x32_bf16 v[102:105], v[182:185], v[198:201], v[102:105]
	v_mfma_f32_16x16x32_bf16 v[102:105], v[186:189], v[214:217], v[102:105]
	v_mfma_f32_16x16x32_bf16 v[90:93], v[156:159], v[218:221], v[90:93]
	v_mfma_f32_16x16x32_bf16 v[90:93], v[160:163], v[222:225], v[90:93]
	v_mfma_f32_16x16x32_bf16 v[86:89], v[182:185], v[218:221], v[86:89]
	v_mfma_f32_16x16x32_bf16 v[86:89], v[186:189], v[222:225], v[86:89]
	v_mfma_f32_16x16x32_bf16 v[74:77], v[156:159], v[226:229], v[74:77]
	v_mfma_f32_16x16x32_bf16 v[74:77], v[160:163], v[230:233], v[74:77]
	v_mfma_f32_16x16x32_bf16 v[70:73], v[182:185], v[226:229], v[70:73]
	v_mfma_f32_16x16x32_bf16 v[70:73], v[186:189], v[230:233], v[70:73]
	s_setprio 0
	s_barrier
	ds_read_b128 v[190:193], v142 offset:16384
	ds_read_b128 v[194:197], v142 offset:17408
	ds_read_b128 v[198:201], v142 offset:18432
	ds_read_b128 v[214:217], v142 offset:19456
	ds_read_b128 v[218:221], v142 offset:20480
	ds_read_b128 v[222:225], v142 offset:21504
	ds_read_b128 v[226:229], v142 offset:22528
	ds_read_b128 v[230:233], v142 offset:23552
	v_lshl_add_u64 v[202:203], s[20:21], 0, v[0:1]
	s_add_i32 s20, s22, s14
	s_mov_b32 m0, s20
	s_nop 0
	global_load_lds_dwordx4 v[202:203], off
	v_lshl_add_u64 v[234:235], v[202:203], 0, s[72:73]
	s_add_i32 m0, s20, 0x2000
	s_add_i32 s20, s23, s14
	global_load_lds_dwordx4 v[234:235], off
	v_lshl_add_u64 v[234:235], v[202:203], 0, s[28:29]
	s_mov_b32 m0, s20
	s_nop 0
	global_load_lds_dwordx4 v[234:235], off
	v_lshl_add_u64 v[234:235], v[202:203], 0, s[82:83]
	s_add_i32 m0, s20, 0x2000
	s_nop 0
	global_load_lds_dwordx4 v[234:235], off
	v_lshl_add_u64 v[234:235], s[76:77], 0, v[130:131]
	s_mov_b32 m0, s43
	v_lshl_add_u64 v[236:237], v[234:235], 0, s[72:73]
	global_load_lds_dwordx4 v[234:235], off
	s_mov_b32 m0, s46
	s_nop 0
	global_load_lds_dwordx4 v[236:237], off
	s_waitcnt vmcnt(8)
	s_waitcnt lgkmcnt(0)
	s_barrier
	s_setprio 1
	s_waitcnt lgkmcnt(0)
	v_mfma_f32_16x16x32_bf16 v[62:65], v[134:137], v[190:193], v[62:65]
	v_mfma_f32_16x16x32_bf16 v[62:65], v[144:147], v[194:197], v[62:65]
	v_mfma_f32_16x16x32_bf16 v[50:53], v[148:151], v[190:193], v[50:53]
	v_mfma_f32_16x16x32_bf16 v[50:53], v[152:155], v[194:197], v[50:53]
	v_mfma_f32_16x16x32_bf16 v[46:49], v[134:137], v[198:201], v[46:49]
	v_mfma_f32_16x16x32_bf16 v[46:49], v[144:147], v[214:217], v[46:49]
	v_mfma_f32_16x16x32_bf16 v[34:37], v[148:151], v[198:201], v[34:37]
	v_mfma_f32_16x16x32_bf16 v[34:37], v[152:155], v[214:217], v[34:37]
	v_mfma_f32_16x16x32_bf16 v[30:33], v[134:137], v[218:221], v[30:33]
	v_mfma_f32_16x16x32_bf16 v[30:33], v[144:147], v[222:225], v[30:33]
	v_mfma_f32_16x16x32_bf16 v[18:21], v[148:151], v[218:221], v[18:21]
	v_mfma_f32_16x16x32_bf16 v[18:21], v[152:155], v[222:225], v[18:21]
	v_mfma_f32_16x16x32_bf16 v[14:17], v[134:137], v[226:229], v[14:17]
	v_mfma_f32_16x16x32_bf16 v[14:17], v[144:147], v[230:233], v[14:17]
	v_mfma_f32_16x16x32_bf16 v[6:9], v[148:151], v[226:229], v[6:9]
	v_mfma_f32_16x16x32_bf16 v[6:9], v[152:155], v[230:233], v[6:9]
	s_setprio 0
	s_setprio 1
	v_mfma_f32_16x16x32_bf16 v[58:61], v[156:159], v[190:193], v[58:61]
	v_mfma_f32_16x16x32_bf16 v[58:61], v[160:163], v[194:197], v[58:61]
	v_mfma_f32_16x16x32_bf16 v[54:57], v[182:185], v[190:193], v[54:57]
	v_mfma_f32_16x16x32_bf16 v[54:57], v[186:189], v[194:197], v[54:57]
	v_mfma_f32_16x16x32_bf16 v[42:45], v[156:159], v[198:201], v[42:45]
	v_mfma_f32_16x16x32_bf16 v[42:45], v[160:163], v[214:217], v[42:45]
	v_mfma_f32_16x16x32_bf16 v[38:41], v[182:185], v[198:201], v[38:41]
	v_mfma_f32_16x16x32_bf16 v[38:41], v[186:189], v[214:217], v[38:41]
	v_mfma_f32_16x16x32_bf16 v[26:29], v[156:159], v[218:221], v[26:29]
	v_mfma_f32_16x16x32_bf16 v[26:29], v[160:163], v[222:225], v[26:29]
	v_mfma_f32_16x16x32_bf16 v[22:25], v[182:185], v[218:221], v[22:25]
	v_mfma_f32_16x16x32_bf16 v[22:25], v[186:189], v[222:225], v[22:25]
	v_mfma_f32_16x16x32_bf16 v[10:13], v[156:159], v[226:229], v[10:13]
	v_mfma_f32_16x16x32_bf16 v[10:13], v[160:163], v[230:233], v[10:13]
	v_mfma_f32_16x16x32_bf16 v[2:5], v[182:185], v[226:229], v[2:5]
	v_mfma_f32_16x16x32_bf16 v[2:5], v[186:189], v[230:233], v[2:5]
	s_setprio 0
	s_barrier
	s_add_i32 s20, 0, 0x18000
	v_add_u32_e32 v143, s20, v139
	s_add_i32 s21, 0, 0x1c000
	ds_read_b128 v[134:137], v143
	ds_read_b128 v[144:147], v143 offset:1024
	ds_read_b128 v[148:151], v143 offset:2048
	ds_read_b128 v[152:155], v143 offset:3072
	v_add_u32_e32 v143, s21, v139
	ds_read_b128 v[156:159], v143
	ds_read_b128 v[160:163], v143 offset:1024
	ds_read_b128 v[182:185], v143 offset:2048
	ds_read_b128 v[186:189], v143 offset:3072
	ds_read_b128 v[190:193], v142 offset:32768
	ds_read_b128 v[194:197], v142 offset:33792
	ds_read_b128 v[198:201], v142 offset:34816
	ds_read_b128 v[214:217], v142 offset:35840
	ds_read_b128 v[218:221], v142 offset:36864
	ds_read_b128 v[222:225], v142 offset:37888
	ds_read_b128 v[226:229], v142 offset:38912
	ds_read_b128 v[230:233], v142 offset:39936
	s_mov_b32 m0, s47
	v_lshl_add_u64 v[236:237], v[234:235], 0, s[28:29]
	global_load_lds_dwordx4 v[236:237], off
	v_lshl_add_u64 v[236:237], v[234:235], 0, s[82:83]
	s_mov_b32 m0, s78
	s_nop 0
	global_load_lds_dwordx4 v[236:237], off
	s_waitcnt vmcnt(8)
	s_waitcnt lgkmcnt(0)
	s_barrier
	s_setprio 1
	s_waitcnt lgkmcnt(0)
	v_mfma_f32_16x16x32_bf16 v[126:129], v[134:137], v[190:193], v[126:129]
	v_mfma_f32_16x16x32_bf16 v[126:129], v[144:147], v[194:197], v[126:129]
	v_mfma_f32_16x16x32_bf16 v[114:117], v[148:151], v[190:193], v[114:117]
	v_mfma_f32_16x16x32_bf16 v[114:117], v[152:155], v[194:197], v[114:117]
	v_mfma_f32_16x16x32_bf16 v[110:113], v[134:137], v[198:201], v[110:113]
	v_mfma_f32_16x16x32_bf16 v[110:113], v[144:147], v[214:217], v[110:113]
	v_mfma_f32_16x16x32_bf16 v[98:101], v[148:151], v[198:201], v[98:101]
	v_mfma_f32_16x16x32_bf16 v[98:101], v[152:155], v[214:217], v[98:101]
	v_mfma_f32_16x16x32_bf16 v[94:97], v[134:137], v[218:221], v[94:97]
	v_mfma_f32_16x16x32_bf16 v[94:97], v[144:147], v[222:225], v[94:97]
	v_mfma_f32_16x16x32_bf16 v[82:85], v[148:151], v[218:221], v[82:85]
	v_mfma_f32_16x16x32_bf16 v[82:85], v[152:155], v[222:225], v[82:85]
	v_mfma_f32_16x16x32_bf16 v[78:81], v[134:137], v[226:229], v[78:81]
	v_mfma_f32_16x16x32_bf16 v[78:81], v[144:147], v[230:233], v[78:81]
	v_mfma_f32_16x16x32_bf16 v[66:69], v[148:151], v[226:229], v[66:69]
	v_mfma_f32_16x16x32_bf16 v[66:69], v[152:155], v[230:233], v[66:69]
	s_setprio 0
	s_setprio 1
	v_mfma_f32_16x16x32_bf16 v[122:125], v[156:159], v[190:193], v[122:125]
	v_mfma_f32_16x16x32_bf16 v[122:125], v[160:163], v[194:197], v[122:125]
	v_mfma_f32_16x16x32_bf16 v[118:121], v[182:185], v[190:193], v[118:121]
	v_mfma_f32_16x16x32_bf16 v[118:121], v[186:189], v[194:197], v[118:121]
	v_mfma_f32_16x16x32_bf16 v[106:109], v[156:159], v[198:201], v[106:109]
	v_mfma_f32_16x16x32_bf16 v[106:109], v[160:163], v[214:217], v[106:109]
	v_mfma_f32_16x16x32_bf16 v[102:105], v[182:185], v[198:201], v[102:105]
	v_mfma_f32_16x16x32_bf16 v[102:105], v[186:189], v[214:217], v[102:105]
	v_mfma_f32_16x16x32_bf16 v[90:93], v[156:159], v[218:221], v[90:93]
	v_mfma_f32_16x16x32_bf16 v[90:93], v[160:163], v[222:225], v[90:93]
	v_mfma_f32_16x16x32_bf16 v[86:89], v[182:185], v[218:221], v[86:89]
	v_mfma_f32_16x16x32_bf16 v[86:89], v[186:189], v[222:225], v[86:89]
	v_mfma_f32_16x16x32_bf16 v[74:77], v[156:159], v[226:229], v[74:77]
	v_mfma_f32_16x16x32_bf16 v[74:77], v[160:163], v[230:233], v[74:77]
	v_mfma_f32_16x16x32_bf16 v[70:73], v[182:185], v[226:229], v[70:73]
	v_mfma_f32_16x16x32_bf16 v[70:73], v[186:189], v[230:233], v[70:73]
	s_setprio 0
	s_barrier
	ds_read_b128 v[190:193], v142 offset:49152
	ds_read_b128 v[194:197], v142 offset:50176
	ds_read_b128 v[198:201], v142 offset:51200
	ds_read_b128 v[214:217], v142 offset:52224
	ds_read_b128 v[218:221], v142 offset:53248
	ds_read_b128 v[222:225], v142 offset:54272
	ds_read_b128 v[226:229], v142 offset:55296
	ds_read_b128 v[230:233], v142 offset:56320
	s_add_i32 s20, s20, s14
	v_lshl_add_u64 v[236:237], v[202:203], 0, s[34:35]
	s_mov_b32 m0, s20
	s_nop 0
	global_load_lds_dwordx4 v[236:237], off
	v_lshl_add_u64 v[236:237], v[202:203], 0, s[38:39]
	s_add_i32 m0, s20, 0x2000
	s_add_i32 s20, s21, s14
	global_load_lds_dwordx4 v[236:237], off
	v_lshl_add_u64 v[236:237], v[202:203], 0, s[44:45]
	s_mov_b32 m0, s20
	v_lshl_add_u64 v[202:203], v[202:203], 0, s[10:11]
	global_load_lds_dwordx4 v[236:237], off
	s_add_i32 m0, s20, 0x2000
	s_nop 0
	global_load_lds_dwordx4 v[202:203], off
	v_lshl_add_u64 v[202:203], v[234:235], 0, s[34:35]
	s_mov_b32 m0, s79
	s_nop 0
	global_load_lds_dwordx4 v[202:203], off
	v_lshl_add_u64 v[202:203], v[234:235], 0, s[38:39]
	s_mov_b32 m0, s88
	s_nop 0
	global_load_lds_dwordx4 v[202:203], off
	s_waitcnt vmcnt(8)
	s_waitcnt lgkmcnt(0)
	s_barrier
	s_setprio 1
	s_waitcnt lgkmcnt(0)
	v_mfma_f32_16x16x32_bf16 v[62:65], v[134:137], v[190:193], v[62:65]
	v_mfma_f32_16x16x32_bf16 v[62:65], v[144:147], v[194:197], v[62:65]
	v_mfma_f32_16x16x32_bf16 v[50:53], v[148:151], v[190:193], v[50:53]
	v_mfma_f32_16x16x32_bf16 v[50:53], v[152:155], v[194:197], v[50:53]
	v_mfma_f32_16x16x32_bf16 v[46:49], v[134:137], v[198:201], v[46:49]
	v_mfma_f32_16x16x32_bf16 v[46:49], v[144:147], v[214:217], v[46:49]
	v_mfma_f32_16x16x32_bf16 v[34:37], v[148:151], v[198:201], v[34:37]
	v_mfma_f32_16x16x32_bf16 v[34:37], v[152:155], v[214:217], v[34:37]
	v_mfma_f32_16x16x32_bf16 v[30:33], v[134:137], v[218:221], v[30:33]
	v_mfma_f32_16x16x32_bf16 v[30:33], v[144:147], v[222:225], v[30:33]
	v_mfma_f32_16x16x32_bf16 v[18:21], v[148:151], v[218:221], v[18:21]
	v_mfma_f32_16x16x32_bf16 v[18:21], v[152:155], v[222:225], v[18:21]
	v_mfma_f32_16x16x32_bf16 v[14:17], v[134:137], v[226:229], v[14:17]
	v_mfma_f32_16x16x32_bf16 v[14:17], v[144:147], v[230:233], v[14:17]
	v_mfma_f32_16x16x32_bf16 v[6:9], v[148:151], v[226:229], v[6:9]
	v_mfma_f32_16x16x32_bf16 v[6:9], v[152:155], v[230:233], v[6:9]
	s_add_i32 s97, s97, 2
	s_add_u32 s68, s68, 0x100
	s_addc_u32 s69, s69, 0
	s_add_u32 s91, s91, 0x100
	s_addc_u32 s96, s96, 0
	s_setprio 0
	s_setprio 1
	v_mfma_f32_16x16x32_bf16 v[58:61], v[156:159], v[190:193], v[58:61]
	v_mfma_f32_16x16x32_bf16 v[58:61], v[160:163], v[194:197], v[58:61]
	v_mfma_f32_16x16x32_bf16 v[54:57], v[182:185], v[190:193], v[54:57]
	v_mfma_f32_16x16x32_bf16 v[54:57], v[186:189], v[194:197], v[54:57]
	v_mfma_f32_16x16x32_bf16 v[42:45], v[156:159], v[198:201], v[42:45]
	v_mfma_f32_16x16x32_bf16 v[42:45], v[160:163], v[214:217], v[42:45]
	v_mfma_f32_16x16x32_bf16 v[38:41], v[182:185], v[198:201], v[38:41]
	v_mfma_f32_16x16x32_bf16 v[38:41], v[186:189], v[214:217], v[38:41]
	v_mfma_f32_16x16x32_bf16 v[26:29], v[156:159], v[218:221], v[26:29]
	v_mfma_f32_16x16x32_bf16 v[26:29], v[160:163], v[222:225], v[26:29]
	v_mfma_f32_16x16x32_bf16 v[22:25], v[182:185], v[218:221], v[22:25]
	v_mfma_f32_16x16x32_bf16 v[22:25], v[186:189], v[222:225], v[22:25]
	v_mfma_f32_16x16x32_bf16 v[10:13], v[156:159], v[226:229], v[10:13]
	v_mfma_f32_16x16x32_bf16 v[10:13], v[160:163], v[230:233], v[10:13]
	v_mfma_f32_16x16x32_bf16 v[2:5], v[182:185], v[226:229], v[2:5]
	v_mfma_f32_16x16x32_bf16 v[2:5], v[186:189], v[230:233], v[2:5]
	s_setprio 0
	s_barrier
	s_cmp_gt_u32 s97, 13
	s_cbranch_scc0 .LBB0_488
	s_and_b64 vcc, exec, s[48:49]
	s_cbranch_vccz .LBB0_491
	s_barrier

.LBB0_495:
	s_waitcnt lgkmcnt(0)
	v_mul_f32_e32 v146, 0xbfb8aa3b, v144
	v_pk_mul_f32 v[148:149], v[126:127], v[146:147] op_sel_hi:[1,0]
	v_mul_f32_e32 v144, v144, v144
	v_exp_f32_e32 v148, v148
	v_exp_f32_e32 v149, v149
	v_pk_mul_f32 v[122:123], v[126:127], v[122:123]
	v_pk_mul_f32 v[124:125], v[128:129], v[124:125]
	v_pk_mul_f32 v[120:121], v[116:117], v[120:121]
	v_pk_add_f32 v[148:149], v[148:149], 1.0 op_sel_hi:[1,0]
	v_lshl_or_b32 v134, s90, 7, v141
	v_rcp_f32_e32 v148, v148
	v_rcp_f32_e32 v149, v149
	v_ashrrev_i32_e32 v135, 31, v134
	s_mov_b64 s[68:69], -1
	s_and_b64 vcc, exec, s[52:53]
	v_pk_mul_f32 v[126:127], v[144:145], v[148:149] op_sel_hi:[0,1]
	v_pk_mul_f32 v[122:123], v[122:123], v[126:127]
	v_pk_mul_f32 v[126:127], v[128:129], v[146:147] op_sel_hi:[1,0]
	s_nop 0
	v_exp_f32_e32 v126, v126
	v_exp_f32_e32 v127, v127
	s_nop 0
	v_pk_add_f32 v[126:127], v[126:127], 1.0 op_sel_hi:[1,0]
	s_nop 0
	v_rcp_f32_e32 v126, v126
	v_rcp_f32_e32 v127, v127
	s_nop 0
	v_pk_mul_f32 v[126:127], v[144:145], v[126:127] op_sel_hi:[0,1]
	v_pk_mul_f32 v[124:125], v[124:125], v[126:127]
	v_pk_mul_f32 v[126:127], v[114:115], v[146:147] op_sel_hi:[1,0]
	v_pk_mul_f32 v[114:115], v[114:115], v[118:119]
	v_exp_f32_e32 v126, v126
	v_exp_f32_e32 v127, v127
	s_nop 0
	v_pk_add_f32 v[126:127], v[126:127], 1.0 op_sel_hi:[1,0]
	s_nop 0
	v_rcp_f32_e32 v126, v126
	v_rcp_f32_e32 v127, v127
	s_nop 0
	v_pk_mul_f32 v[118:119], v[144:145], v[126:127] op_sel_hi:[0,1]
	v_pk_mul_f32 v[118:119], v[114:115], v[118:119]
	v_pk_mul_f32 v[114:115], v[116:117], v[146:147] op_sel_hi:[1,0]
	s_nop 0
	v_exp_f32_e32 v114, v114
	v_exp_f32_e32 v115, v115
	s_nop 0
	v_pk_add_f32 v[114:115], v[114:115], 1.0 op_sel_hi:[1,0]
	s_nop 0
	v_rcp_f32_e32 v114, v114
	v_rcp_f32_e32 v115, v115
	s_nop 0
	v_pk_mul_f32 v[114:115], v[144:145], v[114:115] op_sel_hi:[0,1]
	v_pk_mul_f32 v[120:121], v[120:121], v[114:115]
	v_cvt_pk_bf16_f32 v114, v122, v123
	v_cvt_pk_bf16_f32 v115, v124, v125
	v_cvt_pk_bf16_f32 v116, v118, v119
	v_mov_b64_e32 v[118:119], s[40:41]
	v_mad_u64_u32 v[118:119], s[20:21], v136, s17, v[118:119]
	v_cvt_pk_bf16_f32 v117, v120, v121
	v_mov_b32_e32 v120, v119
	v_mad_u64_u32 v[120:121], s[20:21], v137, s17, v[120:121]
	v_mov_b32_e32 v119, v120
	v_lshl_add_u64 v[150:151], v[134:135], 1, v[118:119]
	global_store_dwordx4 v[150:151], v[114:117], off sc1
	s_nop 1
	v_or_b32_e32 v114, 16, v136
	v_ashrrev_i32_e32 v115, 31, v114
	s_cbranch_vccnz .LBB0_497
	ds_read_b32 v116, v143 offset:64
	s_mov_b64 s[68:69], 0

.LBB0_499:
	s_waitcnt lgkmcnt(0)
	v_mul_f32_e32 v118, 0xbfb8aa3b, v116
	v_pk_mul_f32 v[120:121], v[110:111], v[118:119] op_sel_hi:[1,0]
	v_mul_f32_e32 v116, v116, v116
	v_exp_f32_e32 v120, v120
	v_exp_f32_e32 v121, v121
	v_pk_mul_f32 v[106:107], v[110:111], v[106:107]
	v_pk_mul_f32 v[108:109], v[112:113], v[108:109]
	v_pk_mul_f32 v[104:105], v[100:101], v[104:105]
	v_pk_add_f32 v[120:121], v[120:121], 1.0 op_sel_hi:[1,0]
	s_mov_b64 s[68:69], -1
	v_rcp_f32_e32 v120, v120
	v_rcp_f32_e32 v121, v121
	s_and_b64 vcc, exec, s[52:53]
	v_pk_mul_f32 v[110:111], v[116:117], v[120:121] op_sel_hi:[0,1]
	v_pk_mul_f32 v[106:107], v[106:107], v[110:111]
	v_pk_mul_f32 v[110:111], v[112:113], v[118:119] op_sel_hi:[1,0]
	s_nop 0
	v_exp_f32_e32 v110, v110
	v_exp_f32_e32 v111, v111
	s_nop 0
	v_pk_add_f32 v[110:111], v[110:111], 1.0 op_sel_hi:[1,0]
	s_nop 0
	v_rcp_f32_e32 v110, v110
	v_rcp_f32_e32 v111, v111
	s_nop 0
	v_pk_mul_f32 v[110:111], v[116:117], v[110:111] op_sel_hi:[0,1]
	v_pk_mul_f32 v[108:109], v[108:109], v[110:111]
	v_pk_mul_f32 v[110:111], v[98:99], v[118:119] op_sel_hi:[1,0]
	v_pk_mul_f32 v[98:99], v[98:99], v[102:103]
	v_exp_f32_e32 v110, v110
	v_exp_f32_e32 v111, v111
	s_nop 0
	v_pk_add_f32 v[110:111], v[110:111], 1.0 op_sel_hi:[1,0]
	s_nop 0
	v_rcp_f32_e32 v110, v110
	v_rcp_f32_e32 v111, v111
	s_nop 0
	v_pk_mul_f32 v[102:103], v[116:117], v[110:111] op_sel_hi:[0,1]
	v_pk_mul_f32 v[102:103], v[98:99], v[102:103]
	v_pk_mul_f32 v[98:99], v[100:101], v[118:119] op_sel_hi:[1,0]
	s_nop 0
	v_exp_f32_e32 v98, v98
	v_exp_f32_e32 v99, v99
	s_nop 0
	v_pk_add_f32 v[98:99], v[98:99], 1.0 op_sel_hi:[1,0]
	s_nop 0
	v_rcp_f32_e32 v98, v98
	v_rcp_f32_e32 v99, v99
	s_nop 0
	v_pk_mul_f32 v[98:99], v[116:117], v[98:99] op_sel_hi:[0,1]
	v_pk_mul_f32 v[104:105], v[104:105], v[98:99]
	v_cvt_pk_bf16_f32 v98, v106, v107
	v_cvt_pk_bf16_f32 v99, v108, v109
	v_cvt_pk_bf16_f32 v100, v102, v103
	v_cvt_pk_bf16_f32 v101, v104, v105
	s_mul_i32 s20, s17, 0x10
	s_mov_b32 s21, 0
	v_lshl_add_u64 v[102:103], s[20:21], 0, v[150:151]
	global_store_dwordx4 v[102:103], v[98:101], off sc1
	s_nop 1
	v_or_b32_e32 v98, 32, v136
	v_ashrrev_i32_e32 v99, 31, v98
	s_cbranch_vccnz .LBB0_501
	ds_read_b32 v100, v143 offset:128
	s_mov_b64 s[68:69], 0

.LBB0_503:
	s_waitcnt lgkmcnt(0)
	v_mul_f32_e32 v102, 0xbfb8aa3b, v100
	v_pk_mul_f32 v[104:105], v[94:95], v[102:103] op_sel_hi:[1,0]
	v_mul_f32_e32 v100, v100, v100
	v_exp_f32_e32 v104, v104
	v_exp_f32_e32 v105, v105
	v_pk_mul_f32 v[90:91], v[94:95], v[90:91]
	v_pk_mul_f32 v[92:93], v[96:97], v[92:93]
	v_pk_mul_f32 v[88:89], v[84:85], v[88:89]
	v_pk_add_f32 v[104:105], v[104:105], 1.0 op_sel_hi:[1,0]
	s_mov_b64 s[68:69], -1
	v_rcp_f32_e32 v104, v104
	v_rcp_f32_e32 v105, v105
	s_and_b64 vcc, exec, s[52:53]
	v_pk_mul_f32 v[94:95], v[100:101], v[104:105] op_sel_hi:[0,1]
	v_pk_mul_f32 v[90:91], v[90:91], v[94:95]
	v_pk_mul_f32 v[94:95], v[96:97], v[102:103] op_sel_hi:[1,0]
	s_nop 0
	v_exp_f32_e32 v94, v94
	v_exp_f32_e32 v95, v95
	s_nop 0
	v_pk_add_f32 v[94:95], v[94:95], 1.0 op_sel_hi:[1,0]
	s_nop 0
	v_rcp_f32_e32 v94, v94
	v_rcp_f32_e32 v95, v95
	s_nop 0
	v_pk_mul_f32 v[94:95], v[100:101], v[94:95] op_sel_hi:[0,1]
	v_pk_mul_f32 v[92:93], v[92:93], v[94:95]
	v_pk_mul_f32 v[94:95], v[82:83], v[102:103] op_sel_hi:[1,0]
	v_pk_mul_f32 v[82:83], v[82:83], v[86:87]
	v_exp_f32_e32 v94, v94
	v_exp_f32_e32 v95, v95
	s_nop 0
	v_pk_add_f32 v[94:95], v[94:95], 1.0 op_sel_hi:[1,0]
	s_nop 0
	v_rcp_f32_e32 v94, v94
	v_rcp_f32_e32 v95, v95
	s_nop 0
	v_pk_mul_f32 v[86:87], v[100:101], v[94:95] op_sel_hi:[0,1]
	v_pk_mul_f32 v[86:87], v[82:83], v[86:87]
	v_pk_mul_f32 v[82:83], v[84:85], v[102:103] op_sel_hi:[1,0]
	s_nop 0
	v_exp_f32_e32 v82, v82
	v_exp_f32_e32 v83, v83
	s_nop 0
	v_pk_add_f32 v[82:83], v[82:83], 1.0 op_sel_hi:[1,0]
	s_nop 0
	v_rcp_f32_e32 v82, v82
	v_rcp_f32_e32 v83, v83
	s_nop 0
	v_pk_mul_f32 v[82:83], v[100:101], v[82:83] op_sel_hi:[0,1]
	v_pk_mul_f32 v[88:89], v[88:89], v[82:83]
	v_cvt_pk_bf16_f32 v82, v90, v91
	v_cvt_pk_bf16_f32 v83, v92, v93
	v_cvt_pk_bf16_f32 v84, v86, v87
	v_cvt_pk_bf16_f32 v85, v88, v89
	s_mul_i32 s20, s17, 0x20
	s_mov_b32 s21, 0
	v_lshl_add_u64 v[86:87], s[20:21], 0, v[150:151]
	global_store_dwordx4 v[86:87], v[82:85], off sc1
	s_nop 1
	v_or_b32_e32 v82, 48, v136
	v_ashrrev_i32_e32 v83, 31, v82
	s_cbranch_vccnz .LBB0_505
	ds_read_b32 v84, v143 offset:192
	s_mov_b64 s[68:69], 0

.LBB0_507:
	s_waitcnt lgkmcnt(0)
	v_mul_f32_e32 v86, 0xbfb8aa3b, v84
	v_pk_mul_f32 v[88:89], v[78:79], v[86:87] op_sel_hi:[1,0]
	v_mul_f32_e32 v84, v84, v84
	v_exp_f32_e32 v88, v88
	v_exp_f32_e32 v89, v89
	v_pk_mul_f32 v[74:75], v[78:79], v[74:75]
	v_pk_mul_f32 v[76:77], v[80:81], v[76:77]
	v_pk_mul_f32 v[72:73], v[68:69], v[72:73]
	v_pk_add_f32 v[88:89], v[88:89], 1.0 op_sel_hi:[1,0]
	s_mov_b64 s[68:69], -1
	v_rcp_f32_e32 v88, v88
	v_rcp_f32_e32 v89, v89
	s_and_b64 vcc, exec, s[52:53]
	v_pk_mul_f32 v[78:79], v[84:85], v[88:89] op_sel_hi:[0,1]
	v_pk_mul_f32 v[74:75], v[74:75], v[78:79]
	v_pk_mul_f32 v[78:79], v[80:81], v[86:87] op_sel_hi:[1,0]
	s_nop 0
	v_exp_f32_e32 v78, v78
	v_exp_f32_e32 v79, v79
	s_nop 0
	v_pk_add_f32 v[78:79], v[78:79], 1.0 op_sel_hi:[1,0]
	s_nop 0
	v_rcp_f32_e32 v78, v78
	v_rcp_f32_e32 v79, v79
	s_nop 0
	v_pk_mul_f32 v[78:79], v[84:85], v[78:79] op_sel_hi:[0,1]
	v_pk_mul_f32 v[76:77], v[76:77], v[78:79]
	v_pk_mul_f32 v[78:79], v[66:67], v[86:87] op_sel_hi:[1,0]
	v_pk_mul_f32 v[66:67], v[66:67], v[70:71]
	v_exp_f32_e32 v78, v78
	v_exp_f32_e32 v79, v79
	s_nop 0
	v_pk_add_f32 v[78:79], v[78:79], 1.0 op_sel_hi:[1,0]
	s_nop 0
	v_rcp_f32_e32 v78, v78
	v_rcp_f32_e32 v79, v79
	s_nop 0
	v_pk_mul_f32 v[70:71], v[84:85], v[78:79] op_sel_hi:[0,1]
	v_pk_mul_f32 v[70:71], v[66:67], v[70:71]
	v_pk_mul_f32 v[66:67], v[68:69], v[86:87] op_sel_hi:[1,0]
	s_nop 0
	v_exp_f32_e32 v66, v66
	v_exp_f32_e32 v67, v67
	s_nop 0
	v_pk_add_f32 v[66:67], v[66:67], 1.0 op_sel_hi:[1,0]
	s_nop 0
	v_rcp_f32_e32 v66, v66
	v_rcp_f32_e32 v67, v67
	s_nop 0
	v_pk_mul_f32 v[66:67], v[84:85], v[66:67] op_sel_hi:[0,1]
	v_pk_mul_f32 v[72:73], v[72:73], v[66:67]
	v_cvt_pk_bf16_f32 v66, v74, v75
	v_cvt_pk_bf16_f32 v67, v76, v77
	v_cvt_pk_bf16_f32 v68, v70, v71
	v_cvt_pk_bf16_f32 v69, v72, v73
	s_mul_i32 s20, s17, 0x30
	s_mov_b32 s21, 0
	v_lshl_add_u64 v[70:71], s[20:21], 0, v[150:151]
	global_store_dwordx4 v[70:71], v[66:69], off sc1
	s_nop 1
	v_add_u32_e32 v66, 0x80, v136
	v_ashrrev_i32_e32 v67, 31, v66
	s_cbranch_vccnz .LBB0_509
	ds_read_b32 v68, v143 offset:512
	s_mov_b64 s[68:69], 0

.LBB0_511:
	s_waitcnt lgkmcnt(0)
	v_mul_f32_e32 v70, 0xbfb8aa3b, v68
	v_pk_mul_f32 v[72:73], v[62:63], v[70:71] op_sel_hi:[1,0]
	v_mul_f32_e32 v68, v68, v68
	v_exp_f32_e32 v72, v72
	v_exp_f32_e32 v73, v73
	v_pk_mul_f32 v[58:59], v[62:63], v[58:59]
	v_pk_mul_f32 v[60:61], v[64:65], v[60:61]
	v_pk_mul_f32 v[56:57], v[52:53], v[56:57]
	v_pk_add_f32 v[72:73], v[72:73], 1.0 op_sel_hi:[1,0]
	s_mov_b64 s[68:69], -1
	v_rcp_f32_e32 v72, v72
	v_rcp_f32_e32 v73, v73
	s_and_b64 vcc, exec, s[52:53]
	v_pk_mul_f32 v[62:63], v[68:69], v[72:73] op_sel_hi:[0,1]
	v_pk_mul_f32 v[58:59], v[58:59], v[62:63]
	v_pk_mul_f32 v[62:63], v[64:65], v[70:71] op_sel_hi:[1,0]
	s_nop 0
	v_exp_f32_e32 v62, v62
	v_exp_f32_e32 v63, v63
	s_nop 0
	v_pk_add_f32 v[62:63], v[62:63], 1.0 op_sel_hi:[1,0]
	s_nop 0
	v_rcp_f32_e32 v62, v62
	v_rcp_f32_e32 v63, v63
	s_nop 0
	v_pk_mul_f32 v[62:63], v[68:69], v[62:63] op_sel_hi:[0,1]
	v_pk_mul_f32 v[60:61], v[60:61], v[62:63]
	v_pk_mul_f32 v[62:63], v[50:51], v[70:71] op_sel_hi:[1,0]
	v_pk_mul_f32 v[50:51], v[50:51], v[54:55]
	v_exp_f32_e32 v62, v62
	v_exp_f32_e32 v63, v63
	s_nop 0
	v_pk_add_f32 v[62:63], v[62:63], 1.0 op_sel_hi:[1,0]
	s_nop 0
	v_rcp_f32_e32 v62, v62
	v_rcp_f32_e32 v63, v63
	s_nop 0
	v_pk_mul_f32 v[54:55], v[68:69], v[62:63] op_sel_hi:[0,1]
	v_pk_mul_f32 v[54:55], v[50:51], v[54:55]
	v_pk_mul_f32 v[50:51], v[52:53], v[70:71] op_sel_hi:[1,0]
	s_nop 0
	v_exp_f32_e32 v50, v50
	v_exp_f32_e32 v51, v51
	s_nop 0
	v_pk_add_f32 v[50:51], v[50:51], 1.0 op_sel_hi:[1,0]
	s_nop 0
	v_rcp_f32_e32 v50, v50
	v_rcp_f32_e32 v51, v51
	s_nop 0
	v_pk_mul_f32 v[50:51], v[68:69], v[50:51] op_sel_hi:[0,1]
	v_pk_mul_f32 v[56:57], v[56:57], v[50:51]
	v_cvt_pk_bf16_f32 v50, v58, v59
	v_cvt_pk_bf16_f32 v51, v60, v61
	v_cvt_pk_bf16_f32 v52, v54, v55
	v_cvt_pk_bf16_f32 v53, v56, v57
	s_mul_i32 s20, s17, 0x80
	s_mov_b32 s21, 0
	v_lshl_add_u64 v[54:55], s[20:21], 0, v[150:151]
	global_store_dwordx4 v[54:55], v[50:53], off sc1
	s_nop 1
	v_add_u32_e32 v50, 0x90, v136
	v_ashrrev_i32_e32 v51, 31, v50
	s_cbranch_vccnz .LBB0_513
	ds_read_b32 v52, v143 offset:576
	s_mov_b64 s[68:69], 0

.LBB0_515:
	s_waitcnt lgkmcnt(0)
	v_mul_f32_e32 v54, 0xbfb8aa3b, v52
	v_pk_mul_f32 v[56:57], v[46:47], v[54:55] op_sel_hi:[1,0]
	v_mul_f32_e32 v52, v52, v52
	v_exp_f32_e32 v56, v56
	v_exp_f32_e32 v57, v57
	v_pk_mul_f32 v[42:43], v[46:47], v[42:43]
	v_pk_mul_f32 v[44:45], v[48:49], v[44:45]
	v_pk_mul_f32 v[40:41], v[36:37], v[40:41]
	v_pk_add_f32 v[56:57], v[56:57], 1.0 op_sel_hi:[1,0]
	s_mov_b64 s[68:69], -1
	v_rcp_f32_e32 v56, v56
	v_rcp_f32_e32 v57, v57
	s_and_b64 vcc, exec, s[52:53]
	v_pk_mul_f32 v[46:47], v[52:53], v[56:57] op_sel_hi:[0,1]
	v_pk_mul_f32 v[42:43], v[42:43], v[46:47]
	v_pk_mul_f32 v[46:47], v[48:49], v[54:55] op_sel_hi:[1,0]
	s_nop 0
	v_exp_f32_e32 v46, v46
	v_exp_f32_e32 v47, v47
	s_nop 0
	v_pk_add_f32 v[46:47], v[46:47], 1.0 op_sel_hi:[1,0]
	s_nop 0
	v_rcp_f32_e32 v46, v46
	v_rcp_f32_e32 v47, v47
	s_nop 0
	v_pk_mul_f32 v[46:47], v[52:53], v[46:47] op_sel_hi:[0,1]
	v_pk_mul_f32 v[44:45], v[44:45], v[46:47]
	v_pk_mul_f32 v[46:47], v[34:35], v[54:55] op_sel_hi:[1,0]
	v_pk_mul_f32 v[34:35], v[34:35], v[38:39]
	v_exp_f32_e32 v46, v46
	v_exp_f32_e32 v47, v47
	s_nop 0
	v_pk_add_f32 v[46:47], v[46:47], 1.0 op_sel_hi:[1,0]
	s_nop 0
	v_rcp_f32_e32 v46, v46
	v_rcp_f32_e32 v47, v47
	s_nop 0
	v_pk_mul_f32 v[38:39], v[52:53], v[46:47] op_sel_hi:[0,1]
	v_pk_mul_f32 v[38:39], v[34:35], v[38:39]
	v_pk_mul_f32 v[34:35], v[36:37], v[54:55] op_sel_hi:[1,0]
	s_nop 0
	v_exp_f32_e32 v34, v34
	v_exp_f32_e32 v35, v35
	s_nop 0
	v_pk_add_f32 v[34:35], v[34:35], 1.0 op_sel_hi:[1,0]
	s_nop 0
	v_rcp_f32_e32 v34, v34
	v_rcp_f32_e32 v35, v35
	s_nop 0
	v_pk_mul_f32 v[34:35], v[52:53], v[34:35] op_sel_hi:[0,1]
	v_pk_mul_f32 v[40:41], v[40:41], v[34:35]
	v_cvt_pk_bf16_f32 v34, v42, v43
	v_cvt_pk_bf16_f32 v35, v44, v45
	v_cvt_pk_bf16_f32 v36, v38, v39
	v_cvt_pk_bf16_f32 v37, v40, v41
	s_mul_i32 s20, s17, 0x90
	s_mov_b32 s21, 0
	v_lshl_add_u64 v[38:39], s[20:21], 0, v[150:151]
	global_store_dwordx4 v[38:39], v[34:37], off sc1
	s_nop 1
	v_add_u32_e32 v34, 0xa0, v136
	v_ashrrev_i32_e32 v35, 31, v34
	s_cbranch_vccnz .LBB0_517
	ds_read_b32 v36, v143 offset:640
	s_mov_b64 s[68:69], 0

.LBB0_519:
	s_waitcnt lgkmcnt(0)
	v_mul_f32_e32 v38, 0xbfb8aa3b, v36
	v_pk_mul_f32 v[40:41], v[30:31], v[38:39] op_sel_hi:[1,0]
	v_mul_f32_e32 v36, v36, v36
	v_exp_f32_e32 v40, v40
	v_exp_f32_e32 v41, v41
	v_pk_mul_f32 v[26:27], v[30:31], v[26:27]
	v_pk_mul_f32 v[28:29], v[32:33], v[28:29]
	v_pk_mul_f32 v[24:25], v[20:21], v[24:25]
	v_pk_add_f32 v[40:41], v[40:41], 1.0 op_sel_hi:[1,0]
	s_mov_b64 s[68:69], -1
	v_rcp_f32_e32 v40, v40
	v_rcp_f32_e32 v41, v41
	s_and_b64 vcc, exec, s[52:53]
	v_pk_mul_f32 v[30:31], v[36:37], v[40:41] op_sel_hi:[0,1]
	v_pk_mul_f32 v[26:27], v[26:27], v[30:31]
	v_pk_mul_f32 v[30:31], v[32:33], v[38:39] op_sel_hi:[1,0]
	s_nop 0
	v_exp_f32_e32 v30, v30
	v_exp_f32_e32 v31, v31
	s_nop 0
	v_pk_add_f32 v[30:31], v[30:31], 1.0 op_sel_hi:[1,0]
	s_nop 0
	v_rcp_f32_e32 v30, v30
	v_rcp_f32_e32 v31, v31
	s_nop 0
	v_pk_mul_f32 v[30:31], v[36:37], v[30:31] op_sel_hi:[0,1]
	v_pk_mul_f32 v[28:29], v[28:29], v[30:31]
	v_pk_mul_f32 v[30:31], v[18:19], v[38:39] op_sel_hi:[1,0]
	v_pk_mul_f32 v[18:19], v[18:19], v[22:23]
	v_exp_f32_e32 v30, v30
	v_exp_f32_e32 v31, v31
	s_nop 0
	v_pk_add_f32 v[30:31], v[30:31], 1.0 op_sel_hi:[1,0]
	s_nop 0
	v_rcp_f32_e32 v30, v30
	v_rcp_f32_e32 v31, v31
	s_nop 0
	v_pk_mul_f32 v[22:23], v[36:37], v[30:31] op_sel_hi:[0,1]
	v_pk_mul_f32 v[22:23], v[18:19], v[22:23]
	v_pk_mul_f32 v[18:19], v[20:21], v[38:39] op_sel_hi:[1,0]
	s_nop 0
	v_exp_f32_e32 v18, v18
	v_exp_f32_e32 v19, v19
	s_nop 0
	v_pk_add_f32 v[18:19], v[18:19], 1.0 op_sel_hi:[1,0]
	s_nop 0
	v_rcp_f32_e32 v18, v18
	v_rcp_f32_e32 v19, v19
	s_nop 0
	v_pk_mul_f32 v[18:19], v[36:37], v[18:19] op_sel_hi:[0,1]
	v_pk_mul_f32 v[24:25], v[24:25], v[18:19]
	v_cvt_pk_bf16_f32 v18, v26, v27
	v_cvt_pk_bf16_f32 v19, v28, v29
	v_cvt_pk_bf16_f32 v20, v22, v23
	v_cvt_pk_bf16_f32 v21, v24, v25
	s_mul_i32 s20, s17, 0xa0
	s_mov_b32 s21, 0
	v_lshl_add_u64 v[22:23], s[20:21], 0, v[150:151]
	global_store_dwordx4 v[22:23], v[18:21], off sc1
	s_nop 1
	v_add_u32_e32 v18, 0xb0, v136
	v_ashrrev_i32_e32 v19, 31, v18
	s_cbranch_vccnz .LBB0_521
	ds_read_b32 v20, v143 offset:704
	s_mov_b64 s[68:69], 0

.LBB0_523:
	s_waitcnt lgkmcnt(0)
	v_mul_f32_e32 v22, 0xbfb8aa3b, v20
	v_pk_mul_f32 v[24:25], v[14:15], v[22:23] op_sel_hi:[1,0]
	v_mul_f32_e32 v20, v20, v20
	v_exp_f32_e32 v24, v24
	v_exp_f32_e32 v25, v25
	v_pk_mul_f32 v[10:11], v[14:15], v[10:11]
	v_pk_mul_f32 v[12:13], v[16:17], v[12:13]
	v_pk_mul_f32 v[2:3], v[6:7], v[2:3]
	v_pk_add_f32 v[24:25], v[24:25], 1.0 op_sel_hi:[1,0]
	v_pk_mul_f32 v[4:5], v[8:9], v[4:5]
	v_rcp_f32_e32 v24, v24
	v_rcp_f32_e32 v25, v25
	s_mov_b64 s[68:69], -1
	s_andn2_b64 vcc, exec, s[54:55]
	v_pk_mul_f32 v[14:15], v[20:21], v[24:25] op_sel_hi:[0,1]
	v_pk_mul_f32 v[10:11], v[10:11], v[14:15]
	v_pk_mul_f32 v[14:15], v[16:17], v[22:23] op_sel_hi:[1,0]
	s_nop 0
	v_exp_f32_e32 v14, v14
	v_exp_f32_e32 v15, v15
	s_nop 0
	v_pk_add_f32 v[14:15], v[14:15], 1.0 op_sel_hi:[1,0]
	s_nop 0
	v_rcp_f32_e32 v14, v14
	v_rcp_f32_e32 v15, v15
	s_nop 0
	v_pk_mul_f32 v[14:15], v[20:21], v[14:15] op_sel_hi:[0,1]
	v_pk_mul_f32 v[12:13], v[12:13], v[14:15]
	v_pk_mul_f32 v[14:15], v[6:7], v[22:23] op_sel_hi:[1,0]
	s_nop 0
	v_exp_f32_e32 v14, v14
	v_exp_f32_e32 v15, v15
	s_nop 0
	v_pk_add_f32 v[14:15], v[14:15], 1.0 op_sel_hi:[1,0]
	s_nop 0
	v_rcp_f32_e32 v14, v14
	v_rcp_f32_e32 v15, v15
	s_nop 0
	v_pk_mul_f32 v[6:7], v[20:21], v[14:15] op_sel_hi:[0,1]
	v_pk_mul_f32 v[6:7], v[2:3], v[6:7]
	v_pk_mul_f32 v[2:3], v[8:9], v[22:23] op_sel_hi:[1,0]
	s_nop 0
	v_exp_f32_e32 v2, v2
	v_exp_f32_e32 v3, v3
	s_nop 0
	v_pk_add_f32 v[2:3], v[2:3], 1.0 op_sel_hi:[1,0]
	s_nop 0
	v_rcp_f32_e32 v2, v2
	v_rcp_f32_e32 v3, v3
	s_nop 0
	v_pk_mul_f32 v[2:3], v[20:21], v[2:3] op_sel_hi:[0,1]
	v_pk_mul_f32 v[8:9], v[4:5], v[2:3]
	v_cvt_pk_bf16_f32 v2, v10, v11
	v_cvt_pk_bf16_f32 v3, v12, v13
	v_cvt_pk_bf16_f32 v4, v6, v7
	v_cvt_pk_bf16_f32 v5, v8, v9
	s_mul_i32 s20, s17, 0xb0
	s_mov_b32 s21, 0
	v_lshl_add_u64 v[6:7], s[20:21], 0, v[150:151]
	global_store_dwordx4 v[6:7], v[2:5], off sc1
	s_cbranch_vccnz .LBB0_484
	s_andn2_b64 vcc, exec, s[6:7]
	s_cbranch_vccnz .LBB0_483
	s_barrier
	s_branch .LBB0_483

.LBB0_603:
	s_ashr_i32 s51, s50, 31
	s_lshl_b64 s[20:21], s[50:51], 18
	s_add_u32 s78, s0, s20
	s_addc_u32 s79, s1, s21
	s_and_b64 s[20:21], s[56:57], exec
	s_cselect_b32 s42, s79, s7
	s_cselect_b32 s43, s78, s6
	s_ashr_i32 s49, s48, 31
	s_lshl_b64 s[20:21], s[48:49], 18
	s_add_u32 s40, s76, s20
	s_addc_u32 s41, s77, s21
	s_and_b64 s[20:21], s[56:57], exec
	s_cselect_b32 s46, s41, s69
	s_cselect_b32 s47, s40, s68
	s_add_u32 s6, s6, 0x20080
	s_addc_u32 s7, s7, 0
	s_add_u32 s49, s68, 0x100
	v_mov_b32_e32 v2, 0
	s_addc_u32 s51, s69, 0
	s_mov_b32 s84, -2
	s_waitcnt lgkmcnt(0)
	s_add_i32 s22, 0, 0x10000
	s_add_i32 s23, 0, 0x14000
	v_add_u32_e32 v150, s22, v139
	v_add_u32_e32 v162, s23, v139
	ds_read_b128 v[134:137], v150
	ds_read_b128 v[142:145], v150 offset:1024
	ds_read_b128 v[146:149], v150 offset:2048
	ds_read_b128 v[150:153], v150 offset:3072
	ds_read_b128 v[154:157], v162
	ds_read_b128 v[158:161], v162 offset:1024
	ds_read_b128 v[182:185], v162 offset:2048
	ds_read_b128 v[186:189], v162 offset:3072
	ds_read_b128 v[190:193], v141
	ds_read_b128 v[194:197], v141 offset:1024
	ds_read_b128 v[198:201], v141 offset:2048
	ds_read_b128 v[214:217], v141 offset:3072
	ds_read_b128 v[218:221], v141 offset:4096
	ds_read_b128 v[222:225], v141 offset:5120
	ds_read_b128 v[226:229], v141 offset:6144
	ds_read_b128 v[230:233], v141 offset:7168
	v_mov_b32_e32 v3, 0
	v_mov_b64_e32 v[4:5], 0
	v_mov_b64_e32 v[6:7], 0
	v_mov_b64_e32 v[8:9], 0
	v_mov_b64_e32 v[10:11], 0
	v_mov_b64_e32 v[12:13], 0
	v_mov_b64_e32 v[14:15], 0
	v_mov_b64_e32 v[16:17], 0
	v_mov_b64_e32 v[18:19], 0
	v_mov_b64_e32 v[20:21], 0
	v_mov_b64_e32 v[22:23], 0
	v_mov_b64_e32 v[24:25], 0
	v_mov_b64_e32 v[26:27], 0
	v_mov_b64_e32 v[28:29], 0
	v_mov_b64_e32 v[30:31], 0
	v_mov_b64_e32 v[32:33], 0
	v_mov_b64_e32 v[34:35], 0
	v_mov_b64_e32 v[36:37], 0
	v_mov_b64_e32 v[38:39], 0
	v_mov_b64_e32 v[40:41], 0
	v_mov_b64_e32 v[42:43], 0
	v_mov_b64_e32 v[44:45], 0
	v_mov_b64_e32 v[46:47], 0
	v_mov_b64_e32 v[48:49], 0
	v_mov_b64_e32 v[50:51], 0
	v_mov_b64_e32 v[52:53], 0
	v_mov_b64_e32 v[54:55], 0
	v_mov_b64_e32 v[56:57], 0
	v_mov_b64_e32 v[58:59], 0
	v_mov_b64_e32 v[60:61], 0
	v_mov_b64_e32 v[62:63], 0
	v_mov_b64_e32 v[64:65], 0
	v_mov_b64_e32 v[66:67], 0
	v_mov_b64_e32 v[68:69], 0
	v_mov_b64_e32 v[70:71], 0
	v_mov_b64_e32 v[72:73], 0
	v_mov_b64_e32 v[74:75], 0
	v_mov_b64_e32 v[76:77], 0
	v_mov_b64_e32 v[78:79], 0
	v_mov_b64_e32 v[80:81], 0
	v_mov_b64_e32 v[82:83], 0
	v_mov_b64_e32 v[84:85], 0
	v_mov_b64_e32 v[86:87], 0
	v_mov_b64_e32 v[88:89], 0
	v_mov_b64_e32 v[90:91], 0
	v_mov_b64_e32 v[92:93], 0
	v_mov_b64_e32 v[94:95], 0
	v_mov_b64_e32 v[96:97], 0
	v_mov_b64_e32 v[98:99], 0
	v_mov_b64_e32 v[100:101], 0
	v_mov_b64_e32 v[102:103], 0
	v_mov_b64_e32 v[104:105], 0
	v_mov_b64_e32 v[106:107], 0
	v_mov_b64_e32 v[108:109], 0
	v_mov_b64_e32 v[110:111], 0
	v_mov_b64_e32 v[112:113], 0
	v_mov_b64_e32 v[114:115], 0
	v_mov_b64_e32 v[116:117], 0
	v_mov_b64_e32 v[118:119], 0
	v_mov_b64_e32 v[120:121], 0
	v_mov_b64_e32 v[122:123], 0
	v_mov_b64_e32 v[124:125], 0
	v_mov_b64_e32 v[126:127], 0
	v_mov_b64_e32 v[128:129], 0
	s_branch .Lmid_604
	.p2alignl 6, 3212836864

.Lmid_604:
	s_add_u32 s20, s6, 0xfffe0080
	s_addc_u32 s21, s7, -1
	s_cmp_eq_u32 s84, 4
	s_cselect_b32 s69, s42, s21
	s_cselect_b32 s68, s43, s20
	s_cselect_b32 s21, s46, s51
	s_cselect_b32 s20, s47, s49
	v_lshl_add_u64 v[162:163], s[6:7], 0, v[132:133]
	s_add_i32 m0, s89, 0xc000
	s_nop 0
	global_load_lds_dwordx4 v[162:163], off
	v_lshl_add_u64 v[162:163], v[162:163], 0, s[64:65]
	s_add_i32 m0, s89, 0xe000
	s_nop 0
	global_load_lds_dwordx4 v[162:163], off
	s_waitcnt vmcnt(8)
	s_waitcnt lgkmcnt(0)
	s_barrier
	s_setprio 1
	s_waitcnt lgkmcnt(0)
	v_mfma_f32_16x16x32_bf16 v[126:129], v[134:137], v[190:193], v[126:129]
	v_mfma_f32_16x16x32_bf16 v[126:129], v[142:145], v[194:197], v[126:129]
	v_mfma_f32_16x16x32_bf16 v[122:125], v[146:149], v[190:193], v[122:125]
	v_mfma_f32_16x16x32_bf16 v[122:125], v[150:153], v[194:197], v[122:125]
	v_mfma_f32_16x16x32_bf16 v[110:113], v[134:137], v[198:201], v[110:113]
	v_mfma_f32_16x16x32_bf16 v[110:113], v[142:145], v[214:217], v[110:113]
	v_mfma_f32_16x16x32_bf16 v[106:109], v[146:149], v[198:201], v[106:109]
	v_mfma_f32_16x16x32_bf16 v[106:109], v[150:153], v[214:217], v[106:109]
	v_mfma_f32_16x16x32_bf16 v[94:97], v[134:137], v[218:221], v[94:97]
	v_mfma_f32_16x16x32_bf16 v[94:97], v[142:145], v[222:225], v[94:97]
	v_mfma_f32_16x16x32_bf16 v[90:93], v[146:149], v[218:221], v[90:93]
	v_mfma_f32_16x16x32_bf16 v[90:93], v[150:153], v[222:225], v[90:93]
	v_mfma_f32_16x16x32_bf16 v[78:81], v[134:137], v[226:229], v[78:81]
	v_mfma_f32_16x16x32_bf16 v[78:81], v[142:145], v[230:233], v[78:81]
	v_mfma_f32_16x16x32_bf16 v[74:77], v[146:149], v[226:229], v[74:77]
	v_mfma_f32_16x16x32_bf16 v[74:77], v[150:153], v[230:233], v[74:77]
	s_setprio 0
	s_setprio 1
	v_mfma_f32_16x16x32_bf16 v[118:121], v[154:157], v[190:193], v[118:121]
	v_mfma_f32_16x16x32_bf16 v[118:121], v[158:161], v[194:197], v[118:121]
	v_mfma_f32_16x16x32_bf16 v[114:117], v[182:185], v[190:193], v[114:117]
	v_mfma_f32_16x16x32_bf16 v[114:117], v[186:189], v[194:197], v[114:117]
	v_mfma_f32_16x16x32_bf16 v[102:105], v[154:157], v[198:201], v[102:105]
	v_mfma_f32_16x16x32_bf16 v[102:105], v[158:161], v[214:217], v[102:105]
	v_mfma_f32_16x16x32_bf16 v[98:101], v[182:185], v[198:201], v[98:101]
	v_mfma_f32_16x16x32_bf16 v[98:101], v[186:189], v[214:217], v[98:101]
	v_mfma_f32_16x16x32_bf16 v[86:89], v[154:157], v[218:221], v[86:89]
	v_mfma_f32_16x16x32_bf16 v[86:89], v[158:161], v[222:225], v[86:89]
	v_mfma_f32_16x16x32_bf16 v[82:85], v[182:185], v[218:221], v[82:85]
	v_mfma_f32_16x16x32_bf16 v[82:85], v[186:189], v[222:225], v[82:85]
	v_mfma_f32_16x16x32_bf16 v[70:73], v[154:157], v[226:229], v[70:73]
	v_mfma_f32_16x16x32_bf16 v[70:73], v[158:161], v[230:233], v[70:73]
	v_mfma_f32_16x16x32_bf16 v[66:69], v[182:185], v[226:229], v[66:69]
	v_mfma_f32_16x16x32_bf16 v[66:69], v[186:189], v[230:233], v[66:69]
	s_setprio 0
	s_barrier
	ds_read_b128 v[190:193], v141 offset:16384
	ds_read_b128 v[194:197], v141 offset:17408
	ds_read_b128 v[198:201], v141 offset:18432
	ds_read_b128 v[214:217], v141 offset:19456
	ds_read_b128 v[218:221], v141 offset:20480
	ds_read_b128 v[222:225], v141 offset:21504
	ds_read_b128 v[226:229], v141 offset:22528
	ds_read_b128 v[230:233], v141 offset:23552
	v_lshl_add_u64 v[162:163], s[20:21], 0, v[0:1]
	s_add_i32 s20, s22, s88
	s_mov_b32 m0, s20
	s_nop 0
	global_load_lds_dwordx4 v[162:163], off
	v_lshl_add_u64 v[202:203], v[162:163], 0, s[64:65]
	s_add_i32 m0, s20, 0x2000
	s_add_i32 s20, s23, s88
	global_load_lds_dwordx4 v[202:203], off
	v_lshl_add_u64 v[202:203], v[162:163], 0, s[72:73]
	s_mov_b32 m0, s20
	s_nop 0
	global_load_lds_dwordx4 v[202:203], off
	v_lshl_add_u64 v[202:203], v[162:163], 0, s[74:75]
	s_add_i32 m0, s20, 0x2000
	s_nop 0
	global_load_lds_dwordx4 v[202:203], off
	v_lshl_add_u64 v[202:203], s[68:69], 0, v[130:131]
	s_mov_b32 m0, s89
	v_lshl_add_u64 v[234:235], v[202:203], 0, s[64:65]
	global_load_lds_dwordx4 v[202:203], off
	s_mov_b32 m0, s90
	s_nop 0
	global_load_lds_dwordx4 v[234:235], off
	s_waitcnt vmcnt(8)
	s_waitcnt lgkmcnt(0)
	s_barrier
	s_setprio 1
	s_waitcnt lgkmcnt(0)
	v_mfma_f32_16x16x32_bf16 v[62:65], v[134:137], v[190:193], v[62:65]
	v_mfma_f32_16x16x32_bf16 v[62:65], v[142:145], v[194:197], v[62:65]
	v_mfma_f32_16x16x32_bf16 v[58:61], v[146:149], v[190:193], v[58:61]
	v_mfma_f32_16x16x32_bf16 v[58:61], v[150:153], v[194:197], v[58:61]
	v_mfma_f32_16x16x32_bf16 v[46:49], v[134:137], v[198:201], v[46:49]
	v_mfma_f32_16x16x32_bf16 v[46:49], v[142:145], v[214:217], v[46:49]
	v_mfma_f32_16x16x32_bf16 v[42:45], v[146:149], v[198:201], v[42:45]
	v_mfma_f32_16x16x32_bf16 v[42:45], v[150:153], v[214:217], v[42:45]
	v_mfma_f32_16x16x32_bf16 v[30:33], v[134:137], v[218:221], v[30:33]
	v_mfma_f32_16x16x32_bf16 v[30:33], v[142:145], v[222:225], v[30:33]
	v_mfma_f32_16x16x32_bf16 v[26:29], v[146:149], v[218:221], v[26:29]
	v_mfma_f32_16x16x32_bf16 v[26:29], v[150:153], v[222:225], v[26:29]
	v_mfma_f32_16x16x32_bf16 v[14:17], v[134:137], v[226:229], v[14:17]
	v_mfma_f32_16x16x32_bf16 v[14:17], v[142:145], v[230:233], v[14:17]
	v_mfma_f32_16x16x32_bf16 v[10:13], v[146:149], v[226:229], v[10:13]
	v_mfma_f32_16x16x32_bf16 v[10:13], v[150:153], v[230:233], v[10:13]
	s_setprio 0
	s_setprio 1
	v_mfma_f32_16x16x32_bf16 v[54:57], v[154:157], v[190:193], v[54:57]
	v_mfma_f32_16x16x32_bf16 v[54:57], v[158:161], v[194:197], v[54:57]
	v_mfma_f32_16x16x32_bf16 v[50:53], v[182:185], v[190:193], v[50:53]
	v_mfma_f32_16x16x32_bf16 v[50:53], v[186:189], v[194:197], v[50:53]
	v_mfma_f32_16x16x32_bf16 v[38:41], v[154:157], v[198:201], v[38:41]
	v_mfma_f32_16x16x32_bf16 v[38:41], v[158:161], v[214:217], v[38:41]
	v_mfma_f32_16x16x32_bf16 v[34:37], v[182:185], v[198:201], v[34:37]
	v_mfma_f32_16x16x32_bf16 v[34:37], v[186:189], v[214:217], v[34:37]
	v_mfma_f32_16x16x32_bf16 v[22:25], v[154:157], v[218:221], v[22:25]
	v_mfma_f32_16x16x32_bf16 v[22:25], v[158:161], v[222:225], v[22:25]
	v_mfma_f32_16x16x32_bf16 v[18:21], v[182:185], v[218:221], v[18:21]
	v_mfma_f32_16x16x32_bf16 v[18:21], v[186:189], v[222:225], v[18:21]
	v_mfma_f32_16x16x32_bf16 v[6:9], v[154:157], v[226:229], v[6:9]
	v_mfma_f32_16x16x32_bf16 v[6:9], v[158:161], v[230:233], v[6:9]
	v_mfma_f32_16x16x32_bf16 v[2:5], v[182:185], v[226:229], v[2:5]
	v_mfma_f32_16x16x32_bf16 v[2:5], v[186:189], v[230:233], v[2:5]
	s_setprio 0
	s_barrier
	s_add_i32 s20, 0, 0x18000
	s_add_i32 s21, 0, 0x1c000
	v_add_u32_e32 v150, s20, v139
	v_add_u32_e32 v186, s21, v139
	ds_read_b128 v[134:137], v150
	ds_read_b128 v[142:145], v150 offset:1024
	ds_read_b128 v[146:149], v150 offset:2048
	ds_read_b128 v[150:153], v150 offset:3072
	ds_read_b128 v[154:157], v186
	ds_read_b128 v[158:161], v186 offset:1024
	ds_read_b128 v[182:185], v186 offset:2048
	ds_read_b128 v[186:189], v186 offset:3072
	ds_read_b128 v[190:193], v141 offset:32768
	ds_read_b128 v[194:197], v141 offset:33792
	ds_read_b128 v[198:201], v141 offset:34816
	ds_read_b128 v[214:217], v141 offset:35840
	ds_read_b128 v[218:221], v141 offset:36864
	ds_read_b128 v[222:225], v141 offset:37888
	ds_read_b128 v[226:229], v141 offset:38912
	ds_read_b128 v[230:233], v141 offset:39936
	s_mov_b32 m0, s91
	v_lshl_add_u64 v[234:235], v[202:203], 0, s[72:73]
	global_load_lds_dwordx4 v[234:235], off
	v_lshl_add_u64 v[234:235], v[202:203], 0, s[74:75]
	s_mov_b32 m0, s96
	s_nop 0
	global_load_lds_dwordx4 v[234:235], off
	s_waitcnt vmcnt(8)
	s_waitcnt lgkmcnt(0)
	s_barrier
	s_setprio 1
	s_waitcnt lgkmcnt(0)
	v_mfma_f32_16x16x32_bf16 v[126:129], v[134:137], v[190:193], v[126:129]
	v_mfma_f32_16x16x32_bf16 v[126:129], v[142:145], v[194:197], v[126:129]
	v_mfma_f32_16x16x32_bf16 v[122:125], v[146:149], v[190:193], v[122:125]
	v_mfma_f32_16x16x32_bf16 v[122:125], v[150:153], v[194:197], v[122:125]
	v_mfma_f32_16x16x32_bf16 v[110:113], v[134:137], v[198:201], v[110:113]
	v_mfma_f32_16x16x32_bf16 v[110:113], v[142:145], v[214:217], v[110:113]
	v_mfma_f32_16x16x32_bf16 v[106:109], v[146:149], v[198:201], v[106:109]
	v_mfma_f32_16x16x32_bf16 v[106:109], v[150:153], v[214:217], v[106:109]
	v_mfma_f32_16x16x32_bf16 v[94:97], v[134:137], v[218:221], v[94:97]
	v_mfma_f32_16x16x32_bf16 v[94:97], v[142:145], v[222:225], v[94:97]
	v_mfma_f32_16x16x32_bf16 v[90:93], v[146:149], v[218:221], v[90:93]
	v_mfma_f32_16x16x32_bf16 v[90:93], v[150:153], v[222:225], v[90:93]
	v_mfma_f32_16x16x32_bf16 v[78:81], v[134:137], v[226:229], v[78:81]
	v_mfma_f32_16x16x32_bf16 v[78:81], v[142:145], v[230:233], v[78:81]
	v_mfma_f32_16x16x32_bf16 v[74:77], v[146:149], v[226:229], v[74:77]
	v_mfma_f32_16x16x32_bf16 v[74:77], v[150:153], v[230:233], v[74:77]
	s_setprio 0
	s_setprio 1
	v_mfma_f32_16x16x32_bf16 v[118:121], v[154:157], v[190:193], v[118:121]
	v_mfma_f32_16x16x32_bf16 v[118:121], v[158:161], v[194:197], v[118:121]
	v_mfma_f32_16x16x32_bf16 v[114:117], v[182:185], v[190:193], v[114:117]
	v_mfma_f32_16x16x32_bf16 v[114:117], v[186:189], v[194:197], v[114:117]
	v_mfma_f32_16x16x32_bf16 v[102:105], v[154:157], v[198:201], v[102:105]
	v_mfma_f32_16x16x32_bf16 v[102:105], v[158:161], v[214:217], v[102:105]
	v_mfma_f32_16x16x32_bf16 v[98:101], v[182:185], v[198:201], v[98:101]
	v_mfma_f32_16x16x32_bf16 v[98:101], v[186:189], v[214:217], v[98:101]
	v_mfma_f32_16x16x32_bf16 v[86:89], v[154:157], v[218:221], v[86:89]
	v_mfma_f32_16x16x32_bf16 v[86:89], v[158:161], v[222:225], v[86:89]
	v_mfma_f32_16x16x32_bf16 v[82:85], v[182:185], v[218:221], v[82:85]
	v_mfma_f32_16x16x32_bf16 v[82:85], v[186:189], v[222:225], v[82:85]
	v_mfma_f32_16x16x32_bf16 v[70:73], v[154:157], v[226:229], v[70:73]
	v_mfma_f32_16x16x32_bf16 v[70:73], v[158:161], v[230:233], v[70:73]
	v_mfma_f32_16x16x32_bf16 v[66:69], v[182:185], v[226:229], v[66:69]
	v_mfma_f32_16x16x32_bf16 v[66:69], v[186:189], v[230:233], v[66:69]
	s_setprio 0
	s_barrier
	ds_read_b128 v[190:193], v141 offset:49152
	ds_read_b128 v[194:197], v141 offset:50176
	ds_read_b128 v[198:201], v141 offset:51200
	ds_read_b128 v[214:217], v141 offset:52224
	ds_read_b128 v[218:221], v141 offset:53248
	ds_read_b128 v[222:225], v141 offset:54272
	ds_read_b128 v[226:229], v141 offset:55296
	ds_read_b128 v[230:233], v141 offset:56320
	s_add_i32 s20, s20, s88
	v_lshl_add_u64 v[234:235], v[162:163], 0, s[34:35]
	s_mov_b32 m0, s20
	s_nop 0
	global_load_lds_dwordx4 v[234:235], off
	v_lshl_add_u64 v[234:235], v[162:163], 0, s[80:81]
	s_add_i32 m0, s20, 0x2000
	s_add_i32 s20, s21, s88
	global_load_lds_dwordx4 v[234:235], off
	v_lshl_add_u64 v[234:235], v[162:163], 0, s[38:39]
	s_mov_b32 m0, s20
	v_lshl_add_u64 v[162:163], v[162:163], 0, s[86:87]
	global_load_lds_dwordx4 v[234:235], off
	s_add_i32 m0, s20, 0x2000
	s_nop 0
	global_load_lds_dwordx4 v[162:163], off
	v_lshl_add_u64 v[162:163], v[202:203], 0, s[34:35]
	s_mov_b32 m0, s97
	s_nop 0
	global_load_lds_dwordx4 v[162:163], off
	v_lshl_add_u64 v[162:163], v[202:203], 0, s[80:81]
	s_mov_b32 m0, s58
	s_nop 0
	global_load_lds_dwordx4 v[162:163], off
	s_waitcnt vmcnt(8)
	s_waitcnt lgkmcnt(0)
	s_barrier
	s_setprio 1
	s_waitcnt lgkmcnt(0)
	v_mfma_f32_16x16x32_bf16 v[62:65], v[134:137], v[190:193], v[62:65]
	v_mfma_f32_16x16x32_bf16 v[62:65], v[142:145], v[194:197], v[62:65]
	v_mfma_f32_16x16x32_bf16 v[58:61], v[146:149], v[190:193], v[58:61]
	v_mfma_f32_16x16x32_bf16 v[58:61], v[150:153], v[194:197], v[58:61]
	v_mfma_f32_16x16x32_bf16 v[46:49], v[134:137], v[198:201], v[46:49]
	v_mfma_f32_16x16x32_bf16 v[46:49], v[142:145], v[214:217], v[46:49]
	v_mfma_f32_16x16x32_bf16 v[42:45], v[146:149], v[198:201], v[42:45]
	v_mfma_f32_16x16x32_bf16 v[42:45], v[150:153], v[214:217], v[42:45]
	v_mfma_f32_16x16x32_bf16 v[30:33], v[134:137], v[218:221], v[30:33]
	v_mfma_f32_16x16x32_bf16 v[30:33], v[142:145], v[222:225], v[30:33]
	v_mfma_f32_16x16x32_bf16 v[26:29], v[146:149], v[218:221], v[26:29]
	v_mfma_f32_16x16x32_bf16 v[26:29], v[150:153], v[222:225], v[26:29]
	v_mfma_f32_16x16x32_bf16 v[14:17], v[134:137], v[226:229], v[14:17]
	v_mfma_f32_16x16x32_bf16 v[14:17], v[142:145], v[230:233], v[14:17]
	v_mfma_f32_16x16x32_bf16 v[10:13], v[146:149], v[226:229], v[10:13]
	v_mfma_f32_16x16x32_bf16 v[10:13], v[150:153], v[230:233], v[10:13]
	s_add_i32 s84, s84, 2
	s_add_u32 s6, s6, 0x100
	s_addc_u32 s7, s7, 0
	s_add_u32 s49, s49, 0x100
	s_addc_u32 s51, s51, 0
	s_setprio 0
	s_setprio 1
	v_mfma_f32_16x16x32_bf16 v[54:57], v[154:157], v[190:193], v[54:57]
	v_mfma_f32_16x16x32_bf16 v[54:57], v[158:161], v[194:197], v[54:57]
	v_mfma_f32_16x16x32_bf16 v[50:53], v[182:185], v[190:193], v[50:53]
	v_mfma_f32_16x16x32_bf16 v[50:53], v[186:189], v[194:197], v[50:53]
	v_mfma_f32_16x16x32_bf16 v[38:41], v[154:157], v[198:201], v[38:41]
	v_mfma_f32_16x16x32_bf16 v[38:41], v[158:161], v[214:217], v[38:41]
	v_mfma_f32_16x16x32_bf16 v[34:37], v[182:185], v[198:201], v[34:37]
	v_mfma_f32_16x16x32_bf16 v[34:37], v[186:189], v[214:217], v[34:37]
	v_mfma_f32_16x16x32_bf16 v[22:25], v[154:157], v[218:221], v[22:25]
	v_mfma_f32_16x16x32_bf16 v[22:25], v[158:161], v[222:225], v[22:25]
	v_mfma_f32_16x16x32_bf16 v[18:21], v[182:185], v[218:221], v[18:21]
	v_mfma_f32_16x16x32_bf16 v[18:21], v[186:189], v[222:225], v[18:21]
	v_mfma_f32_16x16x32_bf16 v[6:9], v[154:157], v[226:229], v[6:9]
	v_mfma_f32_16x16x32_bf16 v[6:9], v[158:161], v[230:233], v[6:9]
	v_mfma_f32_16x16x32_bf16 v[2:5], v[182:185], v[226:229], v[2:5]
	v_mfma_f32_16x16x32_bf16 v[2:5], v[186:189], v[230:233], v[2:5]
	s_setprio 0
	s_barrier
	s_cmp_gt_u32 s84, 5
	s_cbranch_scc0 .LBB0_604
	s_and_b64 vcc, exec, s[52:53]
	s_cbranch_vccz .LBB0_607
	s_barrier

.LBB0_641:
	s_ashr_i32 s51, s50, 31
	s_lshl_b64 s[20:21], s[50:51], 17
	s_add_u32 s52, s18, s20
	s_addc_u32 s53, s19, s21
	s_and_b64 s[20:21], s[54:55], exec
	s_cselect_b32 s51, s53, s61
	s_cselect_b32 s84, s52, s60
	s_ashr_i32 s49, s48, 31
	s_lshl_b64 s[20:21], s[48:49], 17
	s_add_u32 s56, s24, s20
	s_addc_u32 s57, s25, s21
	s_and_b64 s[20:21], s[54:55], exec
	v_mov_b32_e32 v2, 0
	s_cselect_b32 s49, s57, s59
	s_cselect_b32 s85, s56, s58
	s_mov_b64 s[76:77], 0
	s_mov_b64 s[62:63], -1
	s_mov_b64 s[68:69], 0
	v_mov_b32_e32 v3, 0
	v_mov_b64_e32 v[4:5], 0
	v_mov_b64_e32 v[6:7], 0
	v_mov_b64_e32 v[8:9], 0
	v_mov_b64_e32 v[10:11], 0
	v_mov_b64_e32 v[12:13], 0
	v_mov_b64_e32 v[14:15], 0
	v_mov_b64_e32 v[16:17], 0
	v_mov_b64_e32 v[18:19], 0
	v_mov_b64_e32 v[20:21], 0
	v_mov_b64_e32 v[22:23], 0
	v_mov_b64_e32 v[24:25], 0
	v_mov_b64_e32 v[26:27], 0
	v_mov_b64_e32 v[28:29], 0
	v_mov_b64_e32 v[30:31], 0
	v_mov_b64_e32 v[32:33], 0
	v_mov_b64_e32 v[34:35], 0
	v_mov_b64_e32 v[36:37], 0
	v_mov_b64_e32 v[38:39], 0
	v_mov_b64_e32 v[40:41], 0
	v_mov_b64_e32 v[42:43], 0
	v_mov_b64_e32 v[44:45], 0
	v_mov_b64_e32 v[46:47], 0
	v_mov_b64_e32 v[48:49], 0
	v_mov_b64_e32 v[50:51], 0
	v_mov_b64_e32 v[52:53], 0
	v_mov_b64_e32 v[54:55], 0
	v_mov_b64_e32 v[56:57], 0
	v_mov_b64_e32 v[58:59], 0
	v_mov_b64_e32 v[60:61], 0
	v_mov_b64_e32 v[62:63], 0
	v_mov_b64_e32 v[64:65], 0
	v_mov_b64_e32 v[66:67], 0
	v_mov_b64_e32 v[68:69], 0
	v_mov_b64_e32 v[70:71], 0
	v_mov_b64_e32 v[72:73], 0
	v_mov_b64_e32 v[74:75], 0
	v_mov_b64_e32 v[76:77], 0
	v_mov_b64_e32 v[78:79], 0
	v_mov_b64_e32 v[80:81], 0
	v_mov_b64_e32 v[82:83], 0
	v_mov_b64_e32 v[84:85], 0
	v_mov_b64_e32 v[86:87], 0
	v_mov_b64_e32 v[88:89], 0
	v_mov_b64_e32 v[90:91], 0
	v_mov_b64_e32 v[92:93], 0
	v_mov_b64_e32 v[94:95], 0
	v_mov_b64_e32 v[96:97], 0
	v_mov_b64_e32 v[98:99], 0
	v_mov_b64_e32 v[100:101], 0
	v_mov_b64_e32 v[102:103], 0
	v_mov_b64_e32 v[104:105], 0
	v_mov_b64_e32 v[106:107], 0
	v_mov_b64_e32 v[108:109], 0
	v_mov_b64_e32 v[110:111], 0
	v_mov_b64_e32 v[112:113], 0
	v_mov_b64_e32 v[114:115], 0
	v_mov_b64_e32 v[116:117], 0
	v_mov_b64_e32 v[118:119], 0
	v_mov_b64_e32 v[120:121], 0
	v_mov_b64_e32 v[122:123], 0
	v_mov_b64_e32 v[124:125], 0
	v_mov_b64_e32 v[126:127], 0
	v_mov_b64_e32 v[128:129], 0

.LBB0_777:
	s_ashr_i32 s61, s60, 31
	s_lshl_b64 s[20:21], s[60:61], 19
	s_add_u32 s62, s94, s20
	s_addc_u32 s63, s95, s21
	s_and_b64 s[20:21], s[56:57], exec
	s_cselect_b32 s61, s63, s77
	s_cselect_b32 s85, s62, s76
	s_ashr_i32 s59, s58, 31
	s_lshl_b64 s[20:21], s[58:59], 19
	s_add_u32 s68, s15, s20
	s_addc_u32 s69, s42, s21
	s_and_b64 s[20:21], s[56:57], exec
	s_cselect_b32 s59, s69, s79
	s_cselect_b32 s86, s68, s78
	s_add_u32 s76, s76, 0x40080
	s_addc_u32 s77, s77, 0
	s_add_u32 s87, s78, 0x100
	v_mov_b32_e32 v2, 0
	s_addc_u32 vcc_lo, s79, 0
	s_mov_b32 vcc_hi, -2
	s_waitcnt lgkmcnt(0)
	s_add_i32 s22, 0, 0x10000
	s_add_i32 s23, 0, 0x14000
	v_add_u32_e32 v142, s22, v193
	v_add_u32_e32 v158, s23, v193
	ds_read_b128 v[130:133], v142
	ds_read_b128 v[134:137], v142 offset:1024
	ds_read_b128 v[138:141], v142 offset:2048
	ds_read_b128 v[142:145], v142 offset:3072
	ds_read_b128 v[146:149], v158
	ds_read_b128 v[150:153], v158 offset:1024
	ds_read_b128 v[154:157], v158 offset:2048
	ds_read_b128 v[158:161], v158 offset:3072
	ds_read_b128 v[184:187], v196
	ds_read_b128 v[188:191], v196 offset:1024
	ds_read_b128 v[198:201], v196 offset:2048
	ds_read_b128 v[214:217], v196 offset:3072
	ds_read_b128 v[218:221], v196 offset:4096
	ds_read_b128 v[222:225], v196 offset:5120
	ds_read_b128 v[226:229], v196 offset:6144
	ds_read_b128 v[230:233], v196 offset:7168
	v_mov_b32_e32 v3, 0
	v_mov_b64_e32 v[4:5], 0
	v_mov_b64_e32 v[6:7], 0
	v_mov_b64_e32 v[8:9], 0
	v_mov_b64_e32 v[10:11], 0
	v_mov_b64_e32 v[12:13], 0
	v_mov_b64_e32 v[14:15], 0
	v_mov_b64_e32 v[16:17], 0
	v_mov_b64_e32 v[18:19], 0
	v_mov_b64_e32 v[20:21], 0
	v_mov_b64_e32 v[22:23], 0
	v_mov_b64_e32 v[24:25], 0
	v_mov_b64_e32 v[26:27], 0
	v_mov_b64_e32 v[28:29], 0
	v_mov_b64_e32 v[30:31], 0
	v_mov_b64_e32 v[32:33], 0
	v_mov_b64_e32 v[34:35], 0
	v_mov_b64_e32 v[36:37], 0
	v_mov_b64_e32 v[38:39], 0
	v_mov_b64_e32 v[40:41], 0
	v_mov_b64_e32 v[42:43], 0
	v_mov_b64_e32 v[44:45], 0
	v_mov_b64_e32 v[46:47], 0
	v_mov_b64_e32 v[48:49], 0
	v_mov_b64_e32 v[50:51], 0
	v_mov_b64_e32 v[52:53], 0
	v_mov_b64_e32 v[54:55], 0
	v_mov_b64_e32 v[56:57], 0
	v_mov_b64_e32 v[58:59], 0
	v_mov_b64_e32 v[60:61], 0
	v_mov_b64_e32 v[62:63], 0
	v_mov_b64_e32 v[64:65], 0
	v_mov_b64_e32 v[66:67], 0
	v_mov_b64_e32 v[68:69], 0
	v_mov_b64_e32 v[70:71], 0
	v_mov_b64_e32 v[72:73], 0
	v_mov_b64_e32 v[74:75], 0
	v_mov_b64_e32 v[76:77], 0
	v_mov_b64_e32 v[78:79], 0
	v_mov_b64_e32 v[80:81], 0
	v_mov_b64_e32 v[82:83], 0
	v_mov_b64_e32 v[84:85], 0
	v_mov_b64_e32 v[86:87], 0
	v_mov_b64_e32 v[88:89], 0
	v_mov_b64_e32 v[90:91], 0
	v_mov_b64_e32 v[92:93], 0
	v_mov_b64_e32 v[94:95], 0
	v_mov_b64_e32 v[96:97], 0
	v_mov_b64_e32 v[98:99], 0
	v_mov_b64_e32 v[100:101], 0
	v_mov_b64_e32 v[102:103], 0
	v_mov_b64_e32 v[104:105], 0
	v_mov_b64_e32 v[106:107], 0
	v_mov_b64_e32 v[108:109], 0
	v_mov_b64_e32 v[110:111], 0
	v_mov_b64_e32 v[112:113], 0
	v_mov_b64_e32 v[114:115], 0
	v_mov_b64_e32 v[116:117], 0
	v_mov_b64_e32 v[118:119], 0
	v_mov_b64_e32 v[120:121], 0
	v_mov_b64_e32 v[122:123], 0
	v_mov_b64_e32 v[124:125], 0
	v_mov_b64_e32 v[126:127], 0
	v_mov_b64_e32 v[128:129], 0
	s_branch .Lmid_778
	.p2alignl 6, 3212836864

.Lmid_778:
	s_add_u32 s20, s76, 0xfffc0080
	s_addc_u32 s21, s77, -1
	s_cmp_eq_u32 vcc_hi, 12
	s_cselect_b32 s79, s61, s21
	s_cselect_b32 s78, s85, s20
	s_cselect_b32 s21, s59, vcc_lo
	s_cselect_b32 s20, s86, s87
	v_lshl_add_u64 v[202:203], s[76:77], 0, v[182:183]
	s_add_i32 m0, s43, 0xc000
	s_nop 0
	global_load_lds_dwordx4 v[202:203], off
	v_lshl_add_u64 v[202:203], v[202:203], 0, s[72:73]
	s_add_i32 m0, s43, 0xe000
	s_nop 0
	global_load_lds_dwordx4 v[202:203], off
	s_waitcnt vmcnt(8)
	s_waitcnt lgkmcnt(0)
	s_barrier
	s_setprio 1
	s_waitcnt lgkmcnt(0)
	v_mfma_f32_16x16x32_bf16 v[126:129], v[130:133], v[184:187], v[126:129]
	v_mfma_f32_16x16x32_bf16 v[126:129], v[134:137], v[188:191], v[126:129]
	v_mfma_f32_16x16x32_bf16 v[122:125], v[138:141], v[184:187], v[122:125]
	v_mfma_f32_16x16x32_bf16 v[122:125], v[142:145], v[188:191], v[122:125]
	v_mfma_f32_16x16x32_bf16 v[110:113], v[130:133], v[198:201], v[110:113]
	v_mfma_f32_16x16x32_bf16 v[110:113], v[134:137], v[214:217], v[110:113]
	v_mfma_f32_16x16x32_bf16 v[106:109], v[138:141], v[198:201], v[106:109]
	v_mfma_f32_16x16x32_bf16 v[106:109], v[142:145], v[214:217], v[106:109]
	v_mfma_f32_16x16x32_bf16 v[94:97], v[130:133], v[218:221], v[94:97]
	v_mfma_f32_16x16x32_bf16 v[94:97], v[134:137], v[222:225], v[94:97]
	v_mfma_f32_16x16x32_bf16 v[90:93], v[138:141], v[218:221], v[90:93]
	v_mfma_f32_16x16x32_bf16 v[90:93], v[142:145], v[222:225], v[90:93]
	v_mfma_f32_16x16x32_bf16 v[78:81], v[130:133], v[226:229], v[78:81]
	v_mfma_f32_16x16x32_bf16 v[78:81], v[134:137], v[230:233], v[78:81]
	v_mfma_f32_16x16x32_bf16 v[74:77], v[138:141], v[226:229], v[74:77]
	v_mfma_f32_16x16x32_bf16 v[74:77], v[142:145], v[230:233], v[74:77]
	s_setprio 0
	s_setprio 1
	v_mfma_f32_16x16x32_bf16 v[118:121], v[146:149], v[184:187], v[118:121]
	v_mfma_f32_16x16x32_bf16 v[118:121], v[150:153], v[188:191], v[118:121]
	v_mfma_f32_16x16x32_bf16 v[114:117], v[154:157], v[184:187], v[114:117]
	v_mfma_f32_16x16x32_bf16 v[114:117], v[158:161], v[188:191], v[114:117]
	v_mfma_f32_16x16x32_bf16 v[102:105], v[146:149], v[198:201], v[102:105]
	v_mfma_f32_16x16x32_bf16 v[102:105], v[150:153], v[214:217], v[102:105]
	v_mfma_f32_16x16x32_bf16 v[98:101], v[154:157], v[198:201], v[98:101]
	v_mfma_f32_16x16x32_bf16 v[98:101], v[158:161], v[214:217], v[98:101]
	v_mfma_f32_16x16x32_bf16 v[86:89], v[146:149], v[218:221], v[86:89]
	v_mfma_f32_16x16x32_bf16 v[86:89], v[150:153], v[222:225], v[86:89]
	v_mfma_f32_16x16x32_bf16 v[82:85], v[154:157], v[218:221], v[82:85]
	v_mfma_f32_16x16x32_bf16 v[82:85], v[158:161], v[222:225], v[82:85]
	v_mfma_f32_16x16x32_bf16 v[70:73], v[146:149], v[226:229], v[70:73]
	v_mfma_f32_16x16x32_bf16 v[70:73], v[150:153], v[230:233], v[70:73]
	v_mfma_f32_16x16x32_bf16 v[66:69], v[154:157], v[226:229], v[66:69]
	v_mfma_f32_16x16x32_bf16 v[66:69], v[158:161], v[230:233], v[66:69]
	s_setprio 0
	s_barrier
	ds_read_b128 v[184:187], v196 offset:16384
	ds_read_b128 v[188:191], v196 offset:17408
	ds_read_b128 v[198:201], v196 offset:18432
	ds_read_b128 v[214:217], v196 offset:19456
	ds_read_b128 v[218:221], v196 offset:20480
	ds_read_b128 v[222:225], v196 offset:21504
	ds_read_b128 v[226:229], v196 offset:22528
	ds_read_b128 v[230:233], v196 offset:23552
	v_lshl_add_u64 v[202:203], s[20:21], 0, v[0:1]
	s_add_i32 s20, s22, s14
	s_mov_b32 m0, s20
	s_nop 0
	global_load_lds_dwordx4 v[202:203], off
	v_lshl_add_u64 v[234:235], v[202:203], 0, s[72:73]
	s_add_i32 m0, s20, 0x2000
	s_add_i32 s20, s23, s14
	global_load_lds_dwordx4 v[234:235], off
	v_lshl_add_u64 v[234:235], v[202:203], 0, s[28:29]
	s_mov_b32 m0, s20
	s_nop 0
	global_load_lds_dwordx4 v[234:235], off
	v_lshl_add_u64 v[234:235], v[202:203], 0, s[82:83]
	s_add_i32 m0, s20, 0x2000
	s_nop 0
	global_load_lds_dwordx4 v[234:235], off
	v_lshl_add_u64 v[234:235], s[78:79], 0, v[162:163]
	s_mov_b32 m0, s43
	v_lshl_add_u64 v[236:237], v[234:235], 0, s[72:73]
	global_load_lds_dwordx4 v[234:235], off
	s_mov_b32 m0, s46
	s_nop 0
	global_load_lds_dwordx4 v[236:237], off
	s_waitcnt vmcnt(8)
	s_waitcnt lgkmcnt(0)
	s_barrier
	s_setprio 1
	s_waitcnt lgkmcnt(0)
	v_mfma_f32_16x16x32_bf16 v[62:65], v[130:133], v[184:187], v[62:65]
	v_mfma_f32_16x16x32_bf16 v[62:65], v[134:137], v[188:191], v[62:65]
	v_mfma_f32_16x16x32_bf16 v[58:61], v[138:141], v[184:187], v[58:61]
	v_mfma_f32_16x16x32_bf16 v[58:61], v[142:145], v[188:191], v[58:61]
	v_mfma_f32_16x16x32_bf16 v[46:49], v[130:133], v[198:201], v[46:49]
	v_mfma_f32_16x16x32_bf16 v[46:49], v[134:137], v[214:217], v[46:49]
	v_mfma_f32_16x16x32_bf16 v[42:45], v[138:141], v[198:201], v[42:45]
	v_mfma_f32_16x16x32_bf16 v[42:45], v[142:145], v[214:217], v[42:45]
	v_mfma_f32_16x16x32_bf16 v[30:33], v[130:133], v[218:221], v[30:33]
	v_mfma_f32_16x16x32_bf16 v[30:33], v[134:137], v[222:225], v[30:33]
	v_mfma_f32_16x16x32_bf16 v[26:29], v[138:141], v[218:221], v[26:29]
	v_mfma_f32_16x16x32_bf16 v[26:29], v[142:145], v[222:225], v[26:29]
	v_mfma_f32_16x16x32_bf16 v[14:17], v[130:133], v[226:229], v[14:17]
	v_mfma_f32_16x16x32_bf16 v[14:17], v[134:137], v[230:233], v[14:17]
	v_mfma_f32_16x16x32_bf16 v[10:13], v[138:141], v[226:229], v[10:13]
	v_mfma_f32_16x16x32_bf16 v[10:13], v[142:145], v[230:233], v[10:13]
	s_setprio 0
	s_setprio 1
	v_mfma_f32_16x16x32_bf16 v[54:57], v[146:149], v[184:187], v[54:57]
	v_mfma_f32_16x16x32_bf16 v[54:57], v[150:153], v[188:191], v[54:57]
	v_mfma_f32_16x16x32_bf16 v[50:53], v[154:157], v[184:187], v[50:53]
	v_mfma_f32_16x16x32_bf16 v[50:53], v[158:161], v[188:191], v[50:53]
	v_mfma_f32_16x16x32_bf16 v[38:41], v[146:149], v[198:201], v[38:41]
	v_mfma_f32_16x16x32_bf16 v[38:41], v[150:153], v[214:217], v[38:41]
	v_mfma_f32_16x16x32_bf16 v[34:37], v[154:157], v[198:201], v[34:37]
	v_mfma_f32_16x16x32_bf16 v[34:37], v[158:161], v[214:217], v[34:37]
	v_mfma_f32_16x16x32_bf16 v[22:25], v[146:149], v[218:221], v[22:25]
	v_mfma_f32_16x16x32_bf16 v[22:25], v[150:153], v[222:225], v[22:25]
	v_mfma_f32_16x16x32_bf16 v[18:21], v[154:157], v[218:221], v[18:21]
	v_mfma_f32_16x16x32_bf16 v[18:21], v[158:161], v[222:225], v[18:21]
	v_mfma_f32_16x16x32_bf16 v[6:9], v[146:149], v[226:229], v[6:9]
	v_mfma_f32_16x16x32_bf16 v[6:9], v[150:153], v[230:233], v[6:9]
	v_mfma_f32_16x16x32_bf16 v[2:5], v[154:157], v[226:229], v[2:5]
	v_mfma_f32_16x16x32_bf16 v[2:5], v[158:161], v[230:233], v[2:5]
	s_setprio 0
	s_barrier
	s_add_i32 s20, 0, 0x18000
	s_add_i32 s21, 0, 0x1c000
	v_add_u32_e32 v142, s20, v193
	v_add_u32_e32 v158, s21, v193
	ds_read_b128 v[130:133], v142
	ds_read_b128 v[134:137], v142 offset:1024
	ds_read_b128 v[138:141], v142 offset:2048
	ds_read_b128 v[142:145], v142 offset:3072
	ds_read_b128 v[146:149], v158
	ds_read_b128 v[150:153], v158 offset:1024
	ds_read_b128 v[154:157], v158 offset:2048
	ds_read_b128 v[158:161], v158 offset:3072
	ds_read_b128 v[184:187], v196 offset:32768
	ds_read_b128 v[188:191], v196 offset:33792
	ds_read_b128 v[198:201], v196 offset:34816
	ds_read_b128 v[214:217], v196 offset:35840
	ds_read_b128 v[218:221], v196 offset:36864
	ds_read_b128 v[222:225], v196 offset:37888
	ds_read_b128 v[226:229], v196 offset:38912
	ds_read_b128 v[230:233], v196 offset:39936
	s_mov_b32 m0, s47
	v_lshl_add_u64 v[236:237], v[234:235], 0, s[28:29]
	global_load_lds_dwordx4 v[236:237], off
	v_lshl_add_u64 v[236:237], v[234:235], 0, s[82:83]
	s_mov_b32 m0, s88
	s_nop 0
	global_load_lds_dwordx4 v[236:237], off
	s_waitcnt vmcnt(8)
	s_waitcnt lgkmcnt(0)
	s_barrier
	s_setprio 1
	s_waitcnt lgkmcnt(0)
	v_mfma_f32_16x16x32_bf16 v[126:129], v[130:133], v[184:187], v[126:129]
	v_mfma_f32_16x16x32_bf16 v[126:129], v[134:137], v[188:191], v[126:129]
	v_mfma_f32_16x16x32_bf16 v[122:125], v[138:141], v[184:187], v[122:125]
	v_mfma_f32_16x16x32_bf16 v[122:125], v[142:145], v[188:191], v[122:125]
	v_mfma_f32_16x16x32_bf16 v[110:113], v[130:133], v[198:201], v[110:113]
	v_mfma_f32_16x16x32_bf16 v[110:113], v[134:137], v[214:217], v[110:113]
	v_mfma_f32_16x16x32_bf16 v[106:109], v[138:141], v[198:201], v[106:109]
	v_mfma_f32_16x16x32_bf16 v[106:109], v[142:145], v[214:217], v[106:109]
	v_mfma_f32_16x16x32_bf16 v[94:97], v[130:133], v[218:221], v[94:97]
	v_mfma_f32_16x16x32_bf16 v[94:97], v[134:137], v[222:225], v[94:97]
	v_mfma_f32_16x16x32_bf16 v[90:93], v[138:141], v[218:221], v[90:93]
	v_mfma_f32_16x16x32_bf16 v[90:93], v[142:145], v[222:225], v[90:93]
	v_mfma_f32_16x16x32_bf16 v[78:81], v[130:133], v[226:229], v[78:81]
	v_mfma_f32_16x16x32_bf16 v[78:81], v[134:137], v[230:233], v[78:81]
	v_mfma_f32_16x16x32_bf16 v[74:77], v[138:141], v[226:229], v[74:77]
	v_mfma_f32_16x16x32_bf16 v[74:77], v[142:145], v[230:233], v[74:77]
	s_setprio 0
	s_setprio 1
	v_mfma_f32_16x16x32_bf16 v[118:121], v[146:149], v[184:187], v[118:121]
	v_mfma_f32_16x16x32_bf16 v[118:121], v[150:153], v[188:191], v[118:121]
	v_mfma_f32_16x16x32_bf16 v[114:117], v[154:157], v[184:187], v[114:117]
	v_mfma_f32_16x16x32_bf16 v[114:117], v[158:161], v[188:191], v[114:117]
	v_mfma_f32_16x16x32_bf16 v[102:105], v[146:149], v[198:201], v[102:105]
	v_mfma_f32_16x16x32_bf16 v[102:105], v[150:153], v[214:217], v[102:105]
	v_mfma_f32_16x16x32_bf16 v[98:101], v[154:157], v[198:201], v[98:101]
	v_mfma_f32_16x16x32_bf16 v[98:101], v[158:161], v[214:217], v[98:101]
	v_mfma_f32_16x16x32_bf16 v[86:89], v[146:149], v[218:221], v[86:89]
	v_mfma_f32_16x16x32_bf16 v[86:89], v[150:153], v[222:225], v[86:89]
	v_mfma_f32_16x16x32_bf16 v[82:85], v[154:157], v[218:221], v[82:85]
	v_mfma_f32_16x16x32_bf16 v[82:85], v[158:161], v[222:225], v[82:85]
	v_mfma_f32_16x16x32_bf16 v[70:73], v[146:149], v[226:229], v[70:73]
	v_mfma_f32_16x16x32_bf16 v[70:73], v[150:153], v[230:233], v[70:73]
	v_mfma_f32_16x16x32_bf16 v[66:69], v[154:157], v[226:229], v[66:69]
	v_mfma_f32_16x16x32_bf16 v[66:69], v[158:161], v[230:233], v[66:69]
	s_setprio 0
	s_barrier
	ds_read_b128 v[184:187], v196 offset:49152
	ds_read_b128 v[188:191], v196 offset:50176
	ds_read_b128 v[198:201], v196 offset:51200
	ds_read_b128 v[214:217], v196 offset:52224
	ds_read_b128 v[218:221], v196 offset:53248
	ds_read_b128 v[222:225], v196 offset:54272
	ds_read_b128 v[226:229], v196 offset:55296
	ds_read_b128 v[230:233], v196 offset:56320
	s_add_i32 s20, s20, s14
	v_lshl_add_u64 v[236:237], v[202:203], 0, s[34:35]
	s_mov_b32 m0, s20
	s_nop 0
	global_load_lds_dwordx4 v[236:237], off
	v_lshl_add_u64 v[236:237], v[202:203], 0, s[38:39]
	s_add_i32 m0, s20, 0x2000
	s_add_i32 s20, s21, s14
	global_load_lds_dwordx4 v[236:237], off
	v_lshl_add_u64 v[236:237], v[202:203], 0, s[44:45]
	s_mov_b32 m0, s20
	v_lshl_add_u64 v[202:203], v[202:203], 0, s[10:11]
	global_load_lds_dwordx4 v[236:237], off
	s_add_i32 m0, s20, 0x2000
	s_nop 0
	global_load_lds_dwordx4 v[202:203], off
	v_lshl_add_u64 v[202:203], v[234:235], 0, s[34:35]
	s_mov_b32 m0, s89
	s_nop 0
	global_load_lds_dwordx4 v[202:203], off
	v_lshl_add_u64 v[202:203], v[234:235], 0, s[38:39]
	s_mov_b32 m0, s90
	s_nop 0
	global_load_lds_dwordx4 v[202:203], off
	s_waitcnt vmcnt(8)
	s_waitcnt lgkmcnt(0)
	s_barrier
	s_setprio 1
	s_waitcnt lgkmcnt(0)
	v_mfma_f32_16x16x32_bf16 v[62:65], v[130:133], v[184:187], v[62:65]
	v_mfma_f32_16x16x32_bf16 v[62:65], v[134:137], v[188:191], v[62:65]
	v_mfma_f32_16x16x32_bf16 v[58:61], v[138:141], v[184:187], v[58:61]
	v_mfma_f32_16x16x32_bf16 v[58:61], v[142:145], v[188:191], v[58:61]
	v_mfma_f32_16x16x32_bf16 v[46:49], v[130:133], v[198:201], v[46:49]
	v_mfma_f32_16x16x32_bf16 v[46:49], v[134:137], v[214:217], v[46:49]
	v_mfma_f32_16x16x32_bf16 v[42:45], v[138:141], v[198:201], v[42:45]
	v_mfma_f32_16x16x32_bf16 v[42:45], v[142:145], v[214:217], v[42:45]
	v_mfma_f32_16x16x32_bf16 v[30:33], v[130:133], v[218:221], v[30:33]
	v_mfma_f32_16x16x32_bf16 v[30:33], v[134:137], v[222:225], v[30:33]
	v_mfma_f32_16x16x32_bf16 v[26:29], v[138:141], v[218:221], v[26:29]
	v_mfma_f32_16x16x32_bf16 v[26:29], v[142:145], v[222:225], v[26:29]
	v_mfma_f32_16x16x32_bf16 v[14:17], v[130:133], v[226:229], v[14:17]
	v_mfma_f32_16x16x32_bf16 v[14:17], v[134:137], v[230:233], v[14:17]
	v_mfma_f32_16x16x32_bf16 v[10:13], v[138:141], v[226:229], v[10:13]
	v_mfma_f32_16x16x32_bf16 v[10:13], v[142:145], v[230:233], v[10:13]
	s_add_i32 vcc_hi, vcc_hi, 2
	s_add_u32 s76, s76, 0x100
	s_addc_u32 s77, s77, 0
	s_add_u32 s87, s87, 0x100
	s_addc_u32 vcc_lo, vcc_lo, 0
	s_setprio 0
	s_setprio 1
	v_mfma_f32_16x16x32_bf16 v[54:57], v[146:149], v[184:187], v[54:57]
	v_mfma_f32_16x16x32_bf16 v[54:57], v[150:153], v[188:191], v[54:57]
	v_mfma_f32_16x16x32_bf16 v[50:53], v[154:157], v[184:187], v[50:53]
	v_mfma_f32_16x16x32_bf16 v[50:53], v[158:161], v[188:191], v[50:53]
	v_mfma_f32_16x16x32_bf16 v[38:41], v[146:149], v[198:201], v[38:41]
	v_mfma_f32_16x16x32_bf16 v[38:41], v[150:153], v[214:217], v[38:41]
	v_mfma_f32_16x16x32_bf16 v[34:37], v[154:157], v[198:201], v[34:37]
	v_mfma_f32_16x16x32_bf16 v[34:37], v[158:161], v[214:217], v[34:37]
	v_mfma_f32_16x16x32_bf16 v[22:25], v[146:149], v[218:221], v[22:25]
	v_mfma_f32_16x16x32_bf16 v[22:25], v[150:153], v[222:225], v[22:25]
	v_mfma_f32_16x16x32_bf16 v[18:21], v[154:157], v[218:221], v[18:21]
	v_mfma_f32_16x16x32_bf16 v[18:21], v[158:161], v[222:225], v[18:21]
	v_mfma_f32_16x16x32_bf16 v[6:9], v[146:149], v[226:229], v[6:9]
	v_mfma_f32_16x16x32_bf16 v[6:9], v[150:153], v[230:233], v[6:9]
	v_mfma_f32_16x16x32_bf16 v[2:5], v[154:157], v[226:229], v[2:5]
	v_mfma_f32_16x16x32_bf16 v[2:5], v[158:161], v[230:233], v[2:5]
	s_setprio 0
	s_barrier
	s_cmp_gt_u32 vcc_hi, 13
	s_cbranch_scc0 .LBB0_778
	s_and_b64 vcc, exec, s[50:51]
	s_cbranch_vccz .LBB0_781
	s_barrier

.LBB0_849:
	s_ashr_i32 s79, s78, 31
	s_lshl_b64 s[20:21], s[78:79], 19
	s_add_u32 s88, s4, s20
	s_addc_u32 s89, s5, s21
	s_and_b64 s[20:21], s[54:55], exec
	s_cselect_b32 s76, s89, s57
	s_cselect_b32 s77, s88, s56
	s_ashr_i32 s69, s68, 31
	s_lshl_b64 s[20:21], s[68:69], 19
	v_readlane_b32 s12, v247, 42
	s_add_u32 s94, s12, s20
	v_readlane_b32 s12, v245, 61
	s_addc_u32 s95, s12, s21
	s_and_b64 s[20:21], s[54:55], exec
	s_cselect_b32 s69, s95, s59
	s_cselect_b32 s79, s94, s58
	s_add_u32 s56, s56, 0x40080
	s_addc_u32 s57, s57, 0
	s_add_u32 s86, s58, 0x100
	v_mov_b32_e32 v2, 0
	s_addc_u32 s87, s59, 0
	s_mov_b32 s91, -2
	s_add_i32 vcc_lo, 0, 0x10000
	v_add_u32_e32 v0, vcc_lo, v145
	s_add_i32 vcc_hi, 0, 0x14000
	ds_read_b128 v[138:141], v0
	ds_read_b128 v[146:149], v0 offset:1024
	ds_read_b128 v[150:153], v0 offset:2048
	ds_read_b128 v[158:161], v0 offset:3072
	v_add_u32_e32 v0, vcc_hi, v145
	ds_read_b128 v[182:185], v0
	ds_read_b128 v[186:189], v0 offset:1024
	ds_read_b128 v[190:193], v0 offset:2048
	ds_read_b128 v[194:197], v0 offset:3072
	ds_read_b128 v[198:201], v157
	ds_read_b128 v[214:217], v157 offset:1024
	ds_read_b128 v[218:221], v157 offset:2048
	ds_read_b128 v[222:225], v157 offset:3072
	ds_read_b128 v[226:229], v157 offset:4096
	ds_read_b128 v[230:233], v157 offset:5120
	ds_read_b128 v[234:237], v157 offset:6144
	ds_read_b128 v[238:241], v157 offset:7168
	v_mov_b32_e32 v3, 0
	v_mov_b64_e32 v[4:5], 0
	v_mov_b64_e32 v[6:7], 0
	v_mov_b64_e32 v[8:9], 0
	v_mov_b64_e32 v[10:11], 0
	v_mov_b64_e32 v[12:13], 0
	v_mov_b64_e32 v[14:15], 0
	v_mov_b64_e32 v[16:17], 0
	v_mov_b64_e32 v[18:19], 0
	v_mov_b64_e32 v[20:21], 0
	v_mov_b64_e32 v[22:23], 0
	v_mov_b64_e32 v[24:25], 0
	v_mov_b64_e32 v[26:27], 0
	v_mov_b64_e32 v[28:29], 0
	v_mov_b64_e32 v[30:31], 0
	v_mov_b64_e32 v[32:33], 0
	v_mov_b64_e32 v[34:35], 0
	v_mov_b64_e32 v[36:37], 0
	v_mov_b64_e32 v[38:39], 0
	v_mov_b64_e32 v[40:41], 0
	v_mov_b64_e32 v[42:43], 0
	v_mov_b64_e32 v[44:45], 0
	v_mov_b64_e32 v[46:47], 0
	v_mov_b64_e32 v[48:49], 0
	v_mov_b64_e32 v[50:51], 0
	v_mov_b64_e32 v[52:53], 0
	v_mov_b64_e32 v[54:55], 0
	v_mov_b64_e32 v[56:57], 0
	v_mov_b64_e32 v[58:59], 0
	v_mov_b64_e32 v[60:61], 0
	v_mov_b64_e32 v[62:63], 0
	v_mov_b64_e32 v[64:65], 0
	v_mov_b64_e32 v[66:67], 0
	v_mov_b64_e32 v[68:69], 0
	v_mov_b64_e32 v[70:71], 0
	v_mov_b64_e32 v[72:73], 0
	v_mov_b64_e32 v[74:75], 0
	v_mov_b64_e32 v[76:77], 0
	v_mov_b64_e32 v[78:79], 0
	v_mov_b64_e32 v[80:81], 0
	v_mov_b64_e32 v[82:83], 0
	v_mov_b64_e32 v[84:85], 0
	v_mov_b64_e32 v[86:87], 0
	v_mov_b64_e32 v[88:89], 0
	v_mov_b64_e32 v[90:91], 0
	v_mov_b64_e32 v[92:93], 0
	v_mov_b64_e32 v[94:95], 0
	v_mov_b64_e32 v[96:97], 0
	v_mov_b64_e32 v[98:99], 0
	v_mov_b64_e32 v[100:101], 0
	v_mov_b64_e32 v[102:103], 0
	v_mov_b64_e32 v[104:105], 0
	v_mov_b64_e32 v[106:107], 0
	v_mov_b64_e32 v[108:109], 0
	v_mov_b64_e32 v[110:111], 0
	v_mov_b64_e32 v[112:113], 0
	v_mov_b64_e32 v[114:115], 0
	v_mov_b64_e32 v[116:117], 0
	v_mov_b64_e32 v[118:119], 0
	v_mov_b64_e32 v[120:121], 0
	v_mov_b64_e32 v[122:123], 0
	v_mov_b64_e32 v[124:125], 0
	v_mov_b64_e32 v[126:127], 0
	v_mov_b64_e32 v[128:129], 0
	s_branch .Lmid_850
	.p2alignl 6, 3212836864

.Lmid_850:
	s_add_u32 s20, s56, 0xfffc0080
	s_addc_u32 s21, s57, -1
	s_cmp_eq_u32 s91, 12
	s_cselect_b32 s59, s76, s21
	s_cselect_b32 s58, s77, s20
	s_cselect_b32 s21, s69, s87
	s_cselect_b32 s20, s79, s86
	v_lshl_add_u64 v[142:143], s[56:57], 0, v[136:137]
	s_add_i32 m0, s15, 0xc000
	s_nop 0
	global_load_lds_dwordx4 v[142:143], off
	v_lshl_add_u64 v[142:143], v[142:143], 0, s[72:73]
	s_add_i32 m0, s15, 0xe000
	s_nop 0
	global_load_lds_dwordx4 v[142:143], off
	s_waitcnt vmcnt(8)
	s_waitcnt lgkmcnt(0)
	s_barrier
	s_setprio 1
	s_waitcnt lgkmcnt(0)
	v_mfma_f32_16x16x32_bf16 v[126:129], v[138:141], v[198:201], v[126:129]
	v_mfma_f32_16x16x32_bf16 v[126:129], v[146:149], v[214:217], v[126:129]
	v_mfma_f32_16x16x32_bf16 v[122:125], v[150:153], v[198:201], v[122:125]
	v_mfma_f32_16x16x32_bf16 v[122:125], v[158:161], v[214:217], v[122:125]
	v_mfma_f32_16x16x32_bf16 v[110:113], v[138:141], v[218:221], v[110:113]
	v_mfma_f32_16x16x32_bf16 v[110:113], v[146:149], v[222:225], v[110:113]
	v_mfma_f32_16x16x32_bf16 v[106:109], v[150:153], v[218:221], v[106:109]
	v_mfma_f32_16x16x32_bf16 v[106:109], v[158:161], v[222:225], v[106:109]
	v_mfma_f32_16x16x32_bf16 v[94:97], v[138:141], v[226:229], v[94:97]
	v_mfma_f32_16x16x32_bf16 v[94:97], v[146:149], v[230:233], v[94:97]
	v_mfma_f32_16x16x32_bf16 v[90:93], v[150:153], v[226:229], v[90:93]
	v_mfma_f32_16x16x32_bf16 v[90:93], v[158:161], v[230:233], v[90:93]
	v_mfma_f32_16x16x32_bf16 v[78:81], v[138:141], v[234:237], v[78:81]
	v_mfma_f32_16x16x32_bf16 v[78:81], v[146:149], v[238:241], v[78:81]
	v_mfma_f32_16x16x32_bf16 v[74:77], v[150:153], v[234:237], v[74:77]
	v_mfma_f32_16x16x32_bf16 v[74:77], v[158:161], v[238:241], v[74:77]
	s_setprio 0
	s_setprio 1
	v_mfma_f32_16x16x32_bf16 v[118:121], v[182:185], v[198:201], v[118:121]
	v_mfma_f32_16x16x32_bf16 v[118:121], v[186:189], v[214:217], v[118:121]
	v_mfma_f32_16x16x32_bf16 v[114:117], v[190:193], v[198:201], v[114:117]
	v_mfma_f32_16x16x32_bf16 v[114:117], v[194:197], v[214:217], v[114:117]
	v_mfma_f32_16x16x32_bf16 v[102:105], v[182:185], v[218:221], v[102:105]
	v_mfma_f32_16x16x32_bf16 v[102:105], v[186:189], v[222:225], v[102:105]
	v_mfma_f32_16x16x32_bf16 v[98:101], v[190:193], v[218:221], v[98:101]
	v_mfma_f32_16x16x32_bf16 v[98:101], v[194:197], v[222:225], v[98:101]
	v_mfma_f32_16x16x32_bf16 v[86:89], v[182:185], v[226:229], v[86:89]
	v_mfma_f32_16x16x32_bf16 v[86:89], v[186:189], v[230:233], v[86:89]
	v_mfma_f32_16x16x32_bf16 v[82:85], v[190:193], v[226:229], v[82:85]
	v_mfma_f32_16x16x32_bf16 v[82:85], v[194:197], v[230:233], v[82:85]
	v_mfma_f32_16x16x32_bf16 v[70:73], v[182:185], v[234:237], v[70:73]
	v_mfma_f32_16x16x32_bf16 v[70:73], v[186:189], v[238:241], v[70:73]
	v_mfma_f32_16x16x32_bf16 v[66:69], v[190:193], v[234:237], v[66:69]
	v_mfma_f32_16x16x32_bf16 v[66:69], v[194:197], v[238:241], v[66:69]
	s_setprio 0
	s_barrier
	ds_read_b128 v[198:201], v157 offset:16384
	ds_read_b128 v[214:217], v157 offset:17408
	ds_read_b128 v[218:221], v157 offset:18432
	ds_read_b128 v[222:225], v157 offset:19456
	ds_read_b128 v[226:229], v157 offset:20480
	ds_read_b128 v[230:233], v157 offset:21504
	ds_read_b128 v[234:237], v157 offset:22528
	ds_read_b128 v[238:241], v157 offset:23552
	v_lshl_add_u64 v[142:143], s[20:21], 0, v[130:131]
	s_add_i32 s20, vcc_lo, s14
	s_mov_b32 m0, s20
	s_nop 0
	global_load_lds_dwordx4 v[142:143], off
	v_lshl_add_u64 v[162:163], v[142:143], 0, s[72:73]
	s_add_i32 m0, s20, 0x2000
	s_add_i32 s20, vcc_hi, s14
	global_load_lds_dwordx4 v[162:163], off
	v_lshl_add_u64 v[162:163], v[142:143], 0, s[28:29]
	s_mov_b32 m0, s20
	s_nop 0
	global_load_lds_dwordx4 v[162:163], off
	v_lshl_add_u64 v[162:163], v[142:143], 0, s[82:83]
	s_add_i32 m0, s20, 0x2000
	s_nop 0
	global_load_lds_dwordx4 v[162:163], off
	v_lshl_add_u64 v[162:163], s[58:59], 0, v[132:133]
	s_mov_b32 m0, s15
	v_lshl_add_u64 v[202:203], v[162:163], 0, s[72:73]
	global_load_lds_dwordx4 v[162:163], off
	s_mov_b32 m0, s42
	s_nop 0
	global_load_lds_dwordx4 v[202:203], off
	s_waitcnt vmcnt(8)
	s_waitcnt lgkmcnt(0)
	s_barrier
	s_setprio 1
	s_waitcnt lgkmcnt(0)
	v_mfma_f32_16x16x32_bf16 v[62:65], v[138:141], v[198:201], v[62:65]
	v_mfma_f32_16x16x32_bf16 v[62:65], v[146:149], v[214:217], v[62:65]
	v_mfma_f32_16x16x32_bf16 v[58:61], v[150:153], v[198:201], v[58:61]
	v_mfma_f32_16x16x32_bf16 v[58:61], v[158:161], v[214:217], v[58:61]
	v_mfma_f32_16x16x32_bf16 v[46:49], v[138:141], v[218:221], v[46:49]
	v_mfma_f32_16x16x32_bf16 v[46:49], v[146:149], v[222:225], v[46:49]
	v_mfma_f32_16x16x32_bf16 v[42:45], v[150:153], v[218:221], v[42:45]
	v_mfma_f32_16x16x32_bf16 v[42:45], v[158:161], v[222:225], v[42:45]
	v_mfma_f32_16x16x32_bf16 v[30:33], v[138:141], v[226:229], v[30:33]
	v_mfma_f32_16x16x32_bf16 v[30:33], v[146:149], v[230:233], v[30:33]
	v_mfma_f32_16x16x32_bf16 v[26:29], v[150:153], v[226:229], v[26:29]
	v_mfma_f32_16x16x32_bf16 v[26:29], v[158:161], v[230:233], v[26:29]
	v_mfma_f32_16x16x32_bf16 v[14:17], v[138:141], v[234:237], v[14:17]
	v_mfma_f32_16x16x32_bf16 v[14:17], v[146:149], v[238:241], v[14:17]
	v_mfma_f32_16x16x32_bf16 v[10:13], v[150:153], v[234:237], v[10:13]
	v_mfma_f32_16x16x32_bf16 v[10:13], v[158:161], v[238:241], v[10:13]
	s_setprio 0
	s_setprio 1
	v_mfma_f32_16x16x32_bf16 v[54:57], v[182:185], v[198:201], v[54:57]
	v_mfma_f32_16x16x32_bf16 v[54:57], v[186:189], v[214:217], v[54:57]
	v_mfma_f32_16x16x32_bf16 v[50:53], v[190:193], v[198:201], v[50:53]
	v_mfma_f32_16x16x32_bf16 v[50:53], v[194:197], v[214:217], v[50:53]
	v_mfma_f32_16x16x32_bf16 v[38:41], v[182:185], v[218:221], v[38:41]
	v_mfma_f32_16x16x32_bf16 v[38:41], v[186:189], v[222:225], v[38:41]
	v_mfma_f32_16x16x32_bf16 v[34:37], v[190:193], v[218:221], v[34:37]
	v_mfma_f32_16x16x32_bf16 v[34:37], v[194:197], v[222:225], v[34:37]
	v_mfma_f32_16x16x32_bf16 v[22:25], v[182:185], v[226:229], v[22:25]
	v_mfma_f32_16x16x32_bf16 v[22:25], v[186:189], v[230:233], v[22:25]
	v_mfma_f32_16x16x32_bf16 v[18:21], v[190:193], v[226:229], v[18:21]
	v_mfma_f32_16x16x32_bf16 v[18:21], v[194:197], v[230:233], v[18:21]
	v_mfma_f32_16x16x32_bf16 v[6:9], v[182:185], v[234:237], v[6:9]
	v_mfma_f32_16x16x32_bf16 v[6:9], v[186:189], v[238:241], v[6:9]
	v_mfma_f32_16x16x32_bf16 v[2:5], v[190:193], v[234:237], v[2:5]
	v_mfma_f32_16x16x32_bf16 v[2:5], v[194:197], v[238:241], v[2:5]
	s_setprio 0
	s_barrier
	s_add_i32 s20, 0, 0x18000
	v_add_u32_e32 v0, s20, v145
	s_add_i32 s21, 0, 0x1c000
	ds_read_b128 v[138:141], v0
	ds_read_b128 v[146:149], v0 offset:1024
	ds_read_b128 v[150:153], v0 offset:2048
	ds_read_b128 v[158:161], v0 offset:3072
	v_add_u32_e32 v0, s21, v145
	ds_read_b128 v[182:185], v0
	ds_read_b128 v[186:189], v0 offset:1024
	ds_read_b128 v[190:193], v0 offset:2048
	ds_read_b128 v[194:197], v0 offset:3072
	ds_read_b128 v[198:201], v157 offset:32768
	ds_read_b128 v[214:217], v157 offset:33792
	ds_read_b128 v[218:221], v157 offset:34816
	ds_read_b128 v[222:225], v157 offset:35840
	ds_read_b128 v[226:229], v157 offset:36864
	ds_read_b128 v[230:233], v157 offset:37888
	ds_read_b128 v[234:237], v157 offset:38912
	ds_read_b128 v[238:241], v157 offset:39936
	s_mov_b32 m0, s43
	v_lshl_add_u64 v[202:203], v[162:163], 0, s[28:29]
	global_load_lds_dwordx4 v[202:203], off
	v_lshl_add_u64 v[202:203], v[162:163], 0, s[82:83]
	s_mov_b32 m0, s46
	s_nop 0
	global_load_lds_dwordx4 v[202:203], off
	s_waitcnt vmcnt(8)
	s_waitcnt lgkmcnt(0)
	s_barrier
	s_setprio 1
	s_waitcnt lgkmcnt(0)
	v_mfma_f32_16x16x32_bf16 v[126:129], v[138:141], v[198:201], v[126:129]
	v_mfma_f32_16x16x32_bf16 v[126:129], v[146:149], v[214:217], v[126:129]
	v_mfma_f32_16x16x32_bf16 v[122:125], v[150:153], v[198:201], v[122:125]
	v_mfma_f32_16x16x32_bf16 v[122:125], v[158:161], v[214:217], v[122:125]
	v_mfma_f32_16x16x32_bf16 v[110:113], v[138:141], v[218:221], v[110:113]
	v_mfma_f32_16x16x32_bf16 v[110:113], v[146:149], v[222:225], v[110:113]
	v_mfma_f32_16x16x32_bf16 v[106:109], v[150:153], v[218:221], v[106:109]
	v_mfma_f32_16x16x32_bf16 v[106:109], v[158:161], v[222:225], v[106:109]
	v_mfma_f32_16x16x32_bf16 v[94:97], v[138:141], v[226:229], v[94:97]
	v_mfma_f32_16x16x32_bf16 v[94:97], v[146:149], v[230:233], v[94:97]
	v_mfma_f32_16x16x32_bf16 v[90:93], v[150:153], v[226:229], v[90:93]
	v_mfma_f32_16x16x32_bf16 v[90:93], v[158:161], v[230:233], v[90:93]
	v_mfma_f32_16x16x32_bf16 v[78:81], v[138:141], v[234:237], v[78:81]
	v_mfma_f32_16x16x32_bf16 v[78:81], v[146:149], v[238:241], v[78:81]
	v_mfma_f32_16x16x32_bf16 v[74:77], v[150:153], v[234:237], v[74:77]
	v_mfma_f32_16x16x32_bf16 v[74:77], v[158:161], v[238:241], v[74:77]
	s_setprio 0
	s_setprio 1
	v_mfma_f32_16x16x32_bf16 v[118:121], v[182:185], v[198:201], v[118:121]
	v_mfma_f32_16x16x32_bf16 v[118:121], v[186:189], v[214:217], v[118:121]
	v_mfma_f32_16x16x32_bf16 v[114:117], v[190:193], v[198:201], v[114:117]
	v_mfma_f32_16x16x32_bf16 v[114:117], v[194:197], v[214:217], v[114:117]
	v_mfma_f32_16x16x32_bf16 v[102:105], v[182:185], v[218:221], v[102:105]
	v_mfma_f32_16x16x32_bf16 v[102:105], v[186:189], v[222:225], v[102:105]
	v_mfma_f32_16x16x32_bf16 v[98:101], v[190:193], v[218:221], v[98:101]
	v_mfma_f32_16x16x32_bf16 v[98:101], v[194:197], v[222:225], v[98:101]
	v_mfma_f32_16x16x32_bf16 v[86:89], v[182:185], v[226:229], v[86:89]
	v_mfma_f32_16x16x32_bf16 v[86:89], v[186:189], v[230:233], v[86:89]
	v_mfma_f32_16x16x32_bf16 v[82:85], v[190:193], v[226:229], v[82:85]
	v_mfma_f32_16x16x32_bf16 v[82:85], v[194:197], v[230:233], v[82:85]
	v_mfma_f32_16x16x32_bf16 v[70:73], v[182:185], v[234:237], v[70:73]
	v_mfma_f32_16x16x32_bf16 v[70:73], v[186:189], v[238:241], v[70:73]
	v_mfma_f32_16x16x32_bf16 v[66:69], v[190:193], v[234:237], v[66:69]
	v_mfma_f32_16x16x32_bf16 v[66:69], v[194:197], v[238:241], v[66:69]
	s_setprio 0
	s_barrier
	ds_read_b128 v[198:201], v157 offset:49152
	ds_read_b128 v[214:217], v157 offset:50176
	ds_read_b128 v[218:221], v157 offset:51200
	ds_read_b128 v[222:225], v157 offset:52224
	ds_read_b128 v[226:229], v157 offset:53248
	ds_read_b128 v[230:233], v157 offset:54272
	ds_read_b128 v[234:237], v157 offset:55296
	ds_read_b128 v[238:241], v157 offset:56320
	s_add_i32 s20, s20, s14
	v_lshl_add_u64 v[202:203], v[142:143], 0, s[34:35]
	s_mov_b32 m0, s20
	s_nop 0
	global_load_lds_dwordx4 v[202:203], off
	v_lshl_add_u64 v[202:203], v[142:143], 0, s[38:39]
	s_add_i32 m0, s20, 0x2000
	s_add_i32 s20, s21, s14
	global_load_lds_dwordx4 v[202:203], off
	v_lshl_add_u64 v[202:203], v[142:143], 0, s[44:45]
	s_mov_b32 m0, s20
	v_lshl_add_u64 v[142:143], v[142:143], 0, s[10:11]
	global_load_lds_dwordx4 v[202:203], off
	s_add_i32 m0, s20, 0x2000
	s_nop 0
	global_load_lds_dwordx4 v[142:143], off
	v_lshl_add_u64 v[142:143], v[162:163], 0, s[34:35]
	s_mov_b32 m0, s47
	s_nop 0
	global_load_lds_dwordx4 v[142:143], off
	v_lshl_add_u64 v[142:143], v[162:163], 0, s[38:39]
	s_mov_b32 m0, s96
	s_nop 0
	global_load_lds_dwordx4 v[142:143], off
	s_waitcnt vmcnt(8)
	s_waitcnt lgkmcnt(0)
	s_barrier
	s_setprio 1
	s_waitcnt lgkmcnt(0)
	v_mfma_f32_16x16x32_bf16 v[62:65], v[138:141], v[198:201], v[62:65]
	v_mfma_f32_16x16x32_bf16 v[62:65], v[146:149], v[214:217], v[62:65]
	v_mfma_f32_16x16x32_bf16 v[58:61], v[150:153], v[198:201], v[58:61]
	v_mfma_f32_16x16x32_bf16 v[58:61], v[158:161], v[214:217], v[58:61]
	v_mfma_f32_16x16x32_bf16 v[46:49], v[138:141], v[218:221], v[46:49]
	v_mfma_f32_16x16x32_bf16 v[46:49], v[146:149], v[222:225], v[46:49]
	v_mfma_f32_16x16x32_bf16 v[42:45], v[150:153], v[218:221], v[42:45]
	v_mfma_f32_16x16x32_bf16 v[42:45], v[158:161], v[222:225], v[42:45]
	v_mfma_f32_16x16x32_bf16 v[30:33], v[138:141], v[226:229], v[30:33]
	v_mfma_f32_16x16x32_bf16 v[30:33], v[146:149], v[230:233], v[30:33]
	v_mfma_f32_16x16x32_bf16 v[26:29], v[150:153], v[226:229], v[26:29]
	v_mfma_f32_16x16x32_bf16 v[26:29], v[158:161], v[230:233], v[26:29]
	v_mfma_f32_16x16x32_bf16 v[14:17], v[138:141], v[234:237], v[14:17]
	v_mfma_f32_16x16x32_bf16 v[14:17], v[146:149], v[238:241], v[14:17]
	v_mfma_f32_16x16x32_bf16 v[10:13], v[150:153], v[234:237], v[10:13]
	v_mfma_f32_16x16x32_bf16 v[10:13], v[158:161], v[238:241], v[10:13]
	s_add_i32 s91, s91, 2
	s_add_u32 s56, s56, 0x100
	s_addc_u32 s57, s57, 0
	s_add_u32 s86, s86, 0x100
	s_addc_u32 s87, s87, 0
	s_setprio 0
	s_setprio 1
	v_mfma_f32_16x16x32_bf16 v[54:57], v[182:185], v[198:201], v[54:57]
	v_mfma_f32_16x16x32_bf16 v[54:57], v[186:189], v[214:217], v[54:57]
	v_mfma_f32_16x16x32_bf16 v[50:53], v[190:193], v[198:201], v[50:53]
	v_mfma_f32_16x16x32_bf16 v[50:53], v[194:197], v[214:217], v[50:53]
	v_mfma_f32_16x16x32_bf16 v[38:41], v[182:185], v[218:221], v[38:41]
	v_mfma_f32_16x16x32_bf16 v[38:41], v[186:189], v[222:225], v[38:41]
	v_mfma_f32_16x16x32_bf16 v[34:37], v[190:193], v[218:221], v[34:37]
	v_mfma_f32_16x16x32_bf16 v[34:37], v[194:197], v[222:225], v[34:37]
	v_mfma_f32_16x16x32_bf16 v[22:25], v[182:185], v[226:229], v[22:25]
	v_mfma_f32_16x16x32_bf16 v[22:25], v[186:189], v[230:233], v[22:25]
	v_mfma_f32_16x16x32_bf16 v[18:21], v[190:193], v[226:229], v[18:21]
	v_mfma_f32_16x16x32_bf16 v[18:21], v[194:197], v[230:233], v[18:21]
	v_mfma_f32_16x16x32_bf16 v[6:9], v[182:185], v[234:237], v[6:9]
	v_mfma_f32_16x16x32_bf16 v[6:9], v[186:189], v[238:241], v[6:9]
	v_mfma_f32_16x16x32_bf16 v[2:5], v[190:193], v[234:237], v[2:5]
	v_mfma_f32_16x16x32_bf16 v[2:5], v[194:197], v[238:241], v[2:5]
	s_setprio 0
	s_barrier
	s_cmp_gt_u32 s91, 13
	s_cbranch_scc0 .LBB0_850
	s_and_b64 vcc, exec, s[62:63]
	s_cbranch_vccz .LBB0_853
	s_barrier

.LBB0_1051:
	s_ashr_i32 s41, s40, 31
	s_lshl_b64 s[20:21], s[40:41], 17
	s_add_u32 s50, s14, s20
	s_addc_u32 s51, s15, s21
	s_and_b64 s[20:21], s[52:53], exec
	s_cselect_b32 s41, s51, s59
	s_cselect_b32 s86, s50, s58
	s_ashr_i32 s49, s48, 31
	s_lshl_b64 s[20:21], s[48:49], 17
	s_add_u32 s54, s42, s20
	s_addc_u32 s55, s43, s21
	s_and_b64 s[20:21], s[52:53], exec
	v_mov_b32_e32 v2, 0
	s_cselect_b32 s49, s55, s57
	s_cselect_b32 s87, s54, s56
	s_mov_b64 s[68:69], 0
	s_mov_b64 s[60:61], -1
	s_mov_b64 s[62:63], 0
	v_mov_b32_e32 v3, 0
	v_mov_b64_e32 v[4:5], 0
	v_mov_b64_e32 v[6:7], 0
	v_mov_b64_e32 v[8:9], 0
	v_mov_b64_e32 v[10:11], 0
	v_mov_b64_e32 v[12:13], 0
	v_mov_b64_e32 v[14:15], 0
	v_mov_b64_e32 v[16:17], 0
	v_mov_b64_e32 v[18:19], 0
	v_mov_b64_e32 v[20:21], 0
	v_mov_b64_e32 v[22:23], 0
	v_mov_b64_e32 v[24:25], 0
	v_mov_b64_e32 v[26:27], 0
	v_mov_b64_e32 v[28:29], 0
	v_mov_b64_e32 v[30:31], 0
	v_mov_b64_e32 v[32:33], 0
	v_mov_b64_e32 v[34:35], 0
	v_mov_b64_e32 v[36:37], 0
	v_mov_b64_e32 v[38:39], 0
	v_mov_b64_e32 v[40:41], 0
	v_mov_b64_e32 v[42:43], 0
	v_mov_b64_e32 v[44:45], 0
	v_mov_b64_e32 v[46:47], 0
	v_mov_b64_e32 v[48:49], 0
	v_mov_b64_e32 v[50:51], 0
	v_mov_b64_e32 v[52:53], 0
	v_mov_b64_e32 v[54:55], 0
	v_mov_b64_e32 v[56:57], 0
	v_mov_b64_e32 v[58:59], 0
	v_mov_b64_e32 v[60:61], 0
	v_mov_b64_e32 v[62:63], 0
	v_mov_b64_e32 v[64:65], 0
	v_mov_b64_e32 v[66:67], 0
	v_mov_b64_e32 v[68:69], 0
	v_mov_b64_e32 v[70:71], 0
	v_mov_b64_e32 v[72:73], 0
	v_mov_b64_e32 v[74:75], 0
	v_mov_b64_e32 v[76:77], 0
	v_mov_b64_e32 v[78:79], 0
	v_mov_b64_e32 v[80:81], 0
	v_mov_b64_e32 v[82:83], 0
	v_mov_b64_e32 v[84:85], 0
	v_mov_b64_e32 v[86:87], 0
	v_mov_b64_e32 v[88:89], 0
	v_mov_b64_e32 v[90:91], 0
	v_mov_b64_e32 v[92:93], 0
	v_mov_b64_e32 v[94:95], 0
	v_mov_b64_e32 v[96:97], 0
	v_mov_b64_e32 v[98:99], 0
	v_mov_b64_e32 v[100:101], 0
	v_mov_b64_e32 v[102:103], 0
	v_mov_b64_e32 v[104:105], 0
	v_mov_b64_e32 v[106:107], 0
	v_mov_b64_e32 v[108:109], 0
	v_mov_b64_e32 v[110:111], 0
	v_mov_b64_e32 v[112:113], 0
	v_mov_b64_e32 v[114:115], 0
	v_mov_b64_e32 v[116:117], 0
	v_mov_b64_e32 v[118:119], 0
	v_mov_b64_e32 v[120:121], 0
	v_mov_b64_e32 v[122:123], 0
	v_mov_b64_e32 v[124:125], 0
	v_mov_b64_e32 v[126:127], 0
	v_mov_b64_e32 v[128:129], 0
	.p2alignl 6, 3212836864
